# EpiUp conv taps: redundant per-DPP wait-state nops removed (first of each run kept)
# speedup vs baseline: 1.0080x; 1.0080x over previous
; #define PG8_LAS __attribute__((address_space(3)))
; __device__ __forceinline__ float dpp_ror1(float x) { float r; asm volatile("s_nop 1\n\tv_mov_b32_dpp %0, %1 row_ror:1 row_mask:0xf bank_mask:0xf" : "=&v"(r) : "v"(x)); return r; }
; __device__ __forceinline__ float dpp_ror2(float x) { float r; asm volatile("s_nop 1\n\tv_mov_b32_dpp %0, %1 row_ror:2 row_mask:0xf bank_mask:0xf" : "=&v"(r) : "v"(x)); return r; }
;     __device__ __forceinline__ void operator()(f32x4 (&acc)[2][2][4][2], const Unit& u, int wr, int wc, int fr_, int fq_) const {
;     ...
;                 for (int n = 0; n < 2; ++n) {
;                     const int ct = bj * HALF + wc * 32 + 8 * fq + 4 * n;
;                     const int cidx = bj * 5632 + jcol + 4 * n;
;                     const f32x4 w0 = *(const f32x4*)(cw + cidx), w1 = *(const f32x4*)(cw + 11264 + cidx), w2 = *(const f32x4*)(cw + 22528 + cidx), b4 = *(const f32x4*)(cb + cidx);
;                     f32x4 pR1 = (f32x4){0.f, 0.f, 0.f, 0.f}, pR2 = pR1;
;                     if (blk) { const f32x4 h14 = *(const PG8_LAS f32x4*)(hal + ((blk - 1) * 2 + 0) * 256 + ct) * rs14, h15 = *(const PG8_LAS f32x4*)(hal + ((blk - 1) * 2 + 1) * 256 + ct) * rs15;
;                         pR1 = h15; pR2 = (fr == 0) ? h14 : h15; }
; #pragma unroll
;                     for (int m = 0; m < 4; ++m) {
;                         const f32x4 U = acc[ai][bj][m][n] * rsr[m];
;                         f32x4 R1, R2;
; #pragma unroll
;                         for (int i = 0; i < 4; ++i) { R1[i] = dpp_ror1(U[i]); R2[i] = dpp_ror2(U[i]); }
;                         const f32x4 U1 = (fr >= 1) ? R1 : pR1, U2 = (fr >= 2) ? R2 : pR2;
;                         const f32x4 C = b4 + w0 * U2 + w1 * U1 + w2 * U;
;                         acc[ai][bj][m][n] = C; pR1 = R1; pR2 = R2;
.LBB0_1718:
	v_cmp_lt_i32_e64 s[8:9], 1, v178
	v_pk_mul_f32 v[126:127], v[126:127], v[192:193] op_sel_hi:[1,0]
	v_pk_mul_f32 v[124:125], v[124:125], v[192:193] op_sel_hi:[1,0]
	v_cmp_lt_i32_e64 s[6:7], 0, v178
	s_nop 1
	v_mov_b32_dpp v199, v124 row_ror:1 row_mask:0xf bank_mask:0xf
	v_mov_b32_dpp v204, v124 row_ror:2 row_mask:0xf bank_mask:0xf
	v_mov_b32_dpp v205, v125 row_ror:1 row_mask:0xf bank_mask:0xf
	v_mov_b32_dpp v206, v125 row_ror:2 row_mask:0xf bank_mask:0xf
	v_mov_b32_dpp v207, v126 row_ror:1 row_mask:0xf bank_mask:0xf
	v_mov_b32_dpp v208, v126 row_ror:2 row_mask:0xf bank_mask:0xf
	v_mov_b32_dpp v209, v127 row_ror:1 row_mask:0xf bank_mask:0xf
	v_mov_b32_dpp v210, v127 row_ror:2 row_mask:0xf bank_mask:0xf
	s_nop 0
	v_cndmask_b32_e64 v202, v187, v204, s[8:9]
	v_cndmask_b32_e64 v200, v189, v208, s[8:9]
	v_cndmask_b32_e64 v201, v193, v210, s[8:9]
	v_cndmask_b32_e64 v203, v191, v206, s[8:9]
	v_cndmask_b32_e64 v174, v174, v199, s[6:7]
	v_cndmask_b32_e64 v175, v175, v205, s[6:7]
	v_cndmask_b32_e64 v172, v172, v207, s[6:7]
	v_cndmask_b32_e64 v173, v173, v209, s[6:7]
	s_waitcnt vmcnt(0)
	v_pk_fma_f32 v[202:203], v[136:137], v[202:203], v[140:141]
	v_pk_fma_f32 v[200:201], v[138:139], v[200:201], v[142:143]
	v_pk_fma_f32 v[174:175], v[128:129], v[174:175], v[202:203]
	v_pk_fma_f32 v[172:173], v[130:131], v[172:173], v[200:201]
	v_pk_fma_f32 v[124:125], v[124:125], v[132:133], v[174:175]
	v_pk_fma_f32 v[126:127], v[126:127], v[134:135], v[172:173]
	s_nop 0
	v_pk_mul_f32 v[122:123], v[122:123], v[190:191] op_sel_hi:[1,0]
	v_pk_mul_f32 v[120:121], v[120:121], v[190:191] op_sel_hi:[1,0]
	s_nop 0
	s_nop 1
	v_mov_b32_dpp v187, v120 row_ror:1 row_mask:0xf bank_mask:0xf
	v_mov_b32_dpp v189, v120 row_ror:2 row_mask:0xf bank_mask:0xf
	v_mov_b32_dpp v191, v121 row_ror:1 row_mask:0xf bank_mask:0xf
	v_mov_b32_dpp v193, v121 row_ror:2 row_mask:0xf bank_mask:0xf
	v_mov_b32_dpp v211, v122 row_ror:1 row_mask:0xf bank_mask:0xf
	v_mov_b32_dpp v212, v122 row_ror:2 row_mask:0xf bank_mask:0xf
	v_mov_b32_dpp v213, v123 row_ror:1 row_mask:0xf bank_mask:0xf
	v_mov_b32_dpp v214, v123 row_ror:2 row_mask:0xf bank_mask:0xf
	s_nop 0
	v_cndmask_b32_e64 v202, v204, v189, s[8:9]
	v_cndmask_b32_e64 v200, v208, v212, s[8:9]
	v_cndmask_b32_e64 v201, v210, v214, s[8:9]
	v_cndmask_b32_e64 v203, v206, v193, s[8:9]
	v_cndmask_b32_e64 v172, v199, v187, s[6:7]
	v_cndmask_b32_e64 v173, v205, v191, s[6:7]
	v_cndmask_b32_e64 v174, v207, v211, s[6:7]
	v_cndmask_b32_e64 v175, v209, v213, s[6:7]
	v_pk_fma_f32 v[202:203], v[136:137], v[202:203], v[140:141]
	v_pk_fma_f32 v[200:201], v[138:139], v[200:201], v[142:143]
	v_pk_fma_f32 v[172:173], v[128:129], v[172:173], v[202:203]
	v_pk_fma_f32 v[174:175], v[130:131], v[174:175], v[200:201]
	v_pk_fma_f32 v[120:121], v[120:121], v[132:133], v[172:173]
	v_pk_fma_f32 v[122:123], v[122:123], v[134:135], v[174:175]
	s_nop 0
	v_pk_mul_f32 v[106:107], v[106:107], v[188:189] op_sel_hi:[1,0]
	v_pk_mul_f32 v[104:105], v[104:105], v[188:189] op_sel_hi:[1,0]
	s_nop 0
	s_nop 1
	v_mov_b32_dpp v199, v104 row_ror:1 row_mask:0xf bank_mask:0xf
	v_mov_b32_dpp v204, v104 row_ror:2 row_mask:0xf bank_mask:0xf
	v_mov_b32_dpp v205, v105 row_ror:1 row_mask:0xf bank_mask:0xf
	v_mov_b32_dpp v206, v105 row_ror:2 row_mask:0xf bank_mask:0xf
	v_mov_b32_dpp v207, v106 row_ror:1 row_mask:0xf bank_mask:0xf
	v_mov_b32_dpp v208, v106 row_ror:2 row_mask:0xf bank_mask:0xf
	v_mov_b32_dpp v209, v107 row_ror:1 row_mask:0xf bank_mask:0xf
	v_mov_b32_dpp v210, v107 row_ror:2 row_mask:0xf bank_mask:0xf
	s_nop 0
	v_cndmask_b32_e64 v202, v189, v204, s[8:9]
	v_cndmask_b32_e64 v200, v212, v208, s[8:9]
	v_cndmask_b32_e64 v201, v214, v210, s[8:9]
	v_cndmask_b32_e64 v203, v193, v206, s[8:9]
	v_cndmask_b32_e64 v172, v187, v199, s[6:7]
	v_cndmask_b32_e64 v173, v191, v205, s[6:7]
	v_cndmask_b32_e64 v174, v211, v207, s[6:7]
	v_cndmask_b32_e64 v175, v213, v209, s[6:7]
	v_pk_fma_f32 v[202:203], v[136:137], v[202:203], v[140:141]
	v_pk_fma_f32 v[200:201], v[138:139], v[200:201], v[142:143]
	v_pk_fma_f32 v[172:173], v[128:129], v[172:173], v[202:203]
	v_pk_fma_f32 v[174:175], v[130:131], v[174:175], v[200:201]
	v_pk_fma_f32 v[104:105], v[104:105], v[132:133], v[172:173]
	v_pk_fma_f32 v[106:107], v[106:107], v[134:135], v[174:175]
	s_nop 0
	v_pk_mul_f32 v[82:83], v[82:83], v[186:187] op_sel_hi:[1,0]
	v_pk_mul_f32 v[80:81], v[80:81], v[186:187] op_sel_hi:[1,0]
	s_nop 0
	s_nop 1
	v_mov_b32_dpp v172, v80 row_ror:1 row_mask:0xf bank_mask:0xf
	v_mov_b32_dpp v187, v80 row_ror:2 row_mask:0xf bank_mask:0xf
	v_mov_b32_dpp v173, v81 row_ror:1 row_mask:0xf bank_mask:0xf
	v_mov_b32_dpp v189, v81 row_ror:2 row_mask:0xf bank_mask:0xf
	v_mov_b32_dpp v174, v82 row_ror:1 row_mask:0xf bank_mask:0xf
	v_mov_b32_dpp v191, v82 row_ror:2 row_mask:0xf bank_mask:0xf
	v_mov_b32_dpp v175, v83 row_ror:1 row_mask:0xf bank_mask:0xf
	v_mov_b32_dpp v193, v83 row_ror:2 row_mask:0xf bank_mask:0xf
	s_nop 0
	v_cndmask_b32_e64 v202, v204, v187, s[8:9]
	v_cndmask_b32_e64 v200, v208, v191, s[8:9]
	v_cndmask_b32_e64 v201, v210, v193, s[8:9]
	v_cndmask_b32_e64 v203, v206, v189, s[8:9]
	v_cndmask_b32_e64 v172, v199, v172, s[6:7]
	v_cndmask_b32_e64 v173, v205, v173, s[6:7]
	v_cndmask_b32_e64 v174, v207, v174, s[6:7]
	v_cndmask_b32_e64 v175, v209, v175, s[6:7]
	v_pk_fma_f32 v[136:137], v[136:137], v[202:203], v[140:141]
	v_pk_fma_f32 v[138:139], v[138:139], v[200:201], v[142:143]
	v_pk_fma_f32 v[128:129], v[128:129], v[172:173], v[136:137]
	v_pk_fma_f32 v[130:131], v[130:131], v[174:175], v[138:139]
	v_pk_fma_f32 v[80:81], v[80:81], v[132:133], v[128:129]
	v_pk_fma_f32 v[82:83], v[82:83], v[134:135], v[130:131]
	s_nop 0
	v_or_b32_e32 v128, 4, v180
	v_ashrrev_i32_e32 v129, 31, v128
	v_lshlrev_b64 v[128:129], 2, v[128:129]
	v_lshl_add_u64 v[172:173], s[42:43], 0, v[128:129]
	global_load_dwordx4 v[136:139], v[164:165], off offset:16
	v_lshl_add_u64 v[174:175], s[44:45], 0, v[128:129]
	global_load_dwordx4 v[132:135], v[172:173], off
	global_load_dwordx4 v[128:131], v[174:175], off
	global_load_dwordx4 v[140:143], v[166:167], off offset:16
	s_and_b64 vcc, exec, s[12:13]
	v_mov_b32_e32 v199, 0
	v_mov_b32_e32 v202, 0
	v_mov_b32_e32 v203, 0
	v_mov_b32_e32 v204, 0
	v_mov_b32_e32 v206, 0
	v_mov_b32_e32 v205, 0
	v_mov_b32_e32 v207, 0
	s_cbranch_vccnz .LBB0_1720
	ds_read_b128 v[198:201], v226 offset:16
	ds_read_b128 v[204:207], v179 offset:16
	v_mov_b32_e32 v202, v196
	v_mov_b32_e32 v203, v196
	s_waitcnt lgkmcnt(1)
	v_pk_mul_f32 v[208:209], v[196:197], v[198:199]
	v_mov_b32_e32 v198, v194
	v_mov_b32_e32 v199, v194
	v_pk_mul_f32 v[200:201], v[202:203], v[200:201]
	s_waitcnt lgkmcnt(0)
	v_pk_mul_f32 v[202:203], v[198:199], v[206:207]
	v_pk_mul_f32 v[198:199], v[194:195], v[204:205]
	v_cndmask_b32_e64 v205, v202, v200, s[10:11]
	v_cndmask_b32_e64 v207, v203, v201, s[10:11]
	v_cndmask_b32_e64 v204, v198, v208, s[10:11]
	v_cndmask_b32_e64 v206, v199, v209, s[10:11]
; #define PG8_LAS __attribute__((address_space(3)))
; __device__ __forceinline__ float dpp_ror1(float x) { float r; asm volatile("s_nop 1\n\tv_mov_b32_dpp %0, %1 row_ror:1 row_mask:0xf bank_mask:0xf" : "=&v"(r) : "v"(x)); return r; }
; __device__ __forceinline__ float dpp_ror2(float x) { float r; asm volatile("s_nop 1\n\tv_mov_b32_dpp %0, %1 row_ror:2 row_mask:0xf bank_mask:0xf" : "=&v"(r) : "v"(x)); return r; }
;     __device__ __forceinline__ void operator()(f32x4 (&acc)[2][2][4][2], const Unit& u, int wr, int wc, int fr_, int fq_) const {
;     ...
;                 for (int n = 0; n < 2; ++n) {
;                     const int ct = bj * HALF + wc * 32 + 8 * fq + 4 * n;
;                     const int cidx = bj * 5632 + jcol + 4 * n;
;                     const f32x4 w0 = *(const f32x4*)(cw + cidx), w1 = *(const f32x4*)(cw + 11264 + cidx), w2 = *(const f32x4*)(cw + 22528 + cidx), b4 = *(const f32x4*)(cb + cidx);
;                     f32x4 pR1 = (f32x4){0.f, 0.f, 0.f, 0.f}, pR2 = pR1;
;                     if (blk) { const f32x4 h14 = *(const PG8_LAS f32x4*)(hal + ((blk - 1) * 2 + 0) * 256 + ct) * rs14, h15 = *(const PG8_LAS f32x4*)(hal + ((blk - 1) * 2 + 1) * 256 + ct) * rs15;
;                         pR1 = h15; pR2 = (fr == 0) ? h14 : h15; }
; #pragma unroll
;                     for (int m = 0; m < 4; ++m) {
;                         const f32x4 U = acc[ai][bj][m][n] * rsr[m];
;                         f32x4 R1, R2;
; #pragma unroll
;                         for (int i = 0; i < 4; ++i) { R1[i] = dpp_ror1(U[i]); R2[i] = dpp_ror2(U[i]); }
;                         const f32x4 U1 = (fr >= 1) ? R1 : pR1, U2 = (fr >= 2) ? R2 : pR2;
;                         const f32x4 C = b4 + w0 * U2 + w1 * U1 + w2 * U;
;                         acc[ai][bj][m][n] = C; pR1 = R1; pR2 = R2;
.LBB0_1720:
	v_mov_b32_e32 v193, v192
	v_mov_b32_e32 v200, v192
	v_mov_b32_e32 v201, v192
	v_pk_mul_f32 v[118:119], v[118:119], v[200:201]
	v_pk_mul_f32 v[116:117], v[116:117], v[192:193]
	v_mov_b32_e32 v187, v186
	s_nop 1
	v_mov_b32_dpp v210, v116 row_ror:1 row_mask:0xf bank_mask:0xf
	v_mov_b32_dpp v211, v116 row_ror:2 row_mask:0xf bank_mask:0xf
	v_mov_b32_dpp v212, v117 row_ror:1 row_mask:0xf bank_mask:0xf
	v_mov_b32_dpp v213, v117 row_ror:2 row_mask:0xf bank_mask:0xf
	v_mov_b32_dpp v214, v118 row_ror:1 row_mask:0xf bank_mask:0xf
	v_mov_b32_dpp v215, v118 row_ror:2 row_mask:0xf bank_mask:0xf
	v_mov_b32_dpp v227, v119 row_ror:1 row_mask:0xf bank_mask:0xf
	v_mov_b32_dpp v228, v119 row_ror:2 row_mask:0xf bank_mask:0xf
	s_nop 0
	v_cndmask_b32_e64 v204, v204, v211, s[8:9]
	v_cndmask_b32_e64 v208, v205, v215, s[8:9]
	v_cndmask_b32_e64 v209, v207, v228, s[8:9]
	v_cndmask_b32_e64 v205, v206, v213, s[8:9]
	v_cndmask_b32_e64 v202, v202, v214, s[6:7]
	v_cndmask_b32_e64 v203, v203, v227, s[6:7]
	v_cndmask_b32_e64 v198, v198, v210, s[6:7]
	v_cndmask_b32_e64 v199, v199, v212, s[6:7]
	s_waitcnt vmcnt(0)
	v_pk_fma_f32 v[206:207], v[138:139], v[208:209], v[142:143]
	v_pk_fma_f32 v[204:205], v[136:137], v[204:205], v[140:141]
	v_pk_fma_f32 v[202:203], v[134:135], v[202:203], v[206:207]
	v_pk_fma_f32 v[198:199], v[132:133], v[198:199], v[204:205]
	v_mov_b32_e32 v191, v190
	v_mov_b32_e32 v189, v188
	v_pk_fma_f32 v[118:119], v[118:119], v[130:131], v[202:203]
	v_pk_fma_f32 v[116:117], v[116:117], v[128:129], v[198:199]
	s_nop 0
	v_mov_b32_e32 v202, v190
	v_mov_b32_e32 v203, v190
	v_pk_mul_f32 v[114:115], v[114:115], v[202:203]
	v_pk_mul_f32 v[112:113], v[112:113], v[190:191]
	s_nop 0
	s_nop 1
	v_mov_b32_dpp v229, v112 row_ror:1 row_mask:0xf bank_mask:0xf
	v_mov_b32_dpp v230, v112 row_ror:2 row_mask:0xf bank_mask:0xf
	v_mov_b32_dpp v231, v113 row_ror:1 row_mask:0xf bank_mask:0xf
	v_mov_b32_dpp v232, v113 row_ror:2 row_mask:0xf bank_mask:0xf
	v_mov_b32_dpp v233, v114 row_ror:1 row_mask:0xf bank_mask:0xf
	v_mov_b32_dpp v234, v114 row_ror:2 row_mask:0xf bank_mask:0xf
	v_mov_b32_dpp v235, v115 row_ror:1 row_mask:0xf bank_mask:0xf
	v_mov_b32_dpp v236, v115 row_ror:2 row_mask:0xf bank_mask:0xf
	s_nop 0
	v_cndmask_b32_e64 v208, v211, v230, s[8:9]
	v_cndmask_b32_e64 v206, v215, v234, s[8:9]
	v_cndmask_b32_e64 v207, v228, v236, s[8:9]
	v_cndmask_b32_e64 v209, v213, v232, s[8:9]
	v_cndmask_b32_e64 v198, v214, v233, s[6:7]
	v_cndmask_b32_e64 v199, v227, v235, s[6:7]
	v_cndmask_b32_e64 v204, v210, v229, s[6:7]
	v_cndmask_b32_e64 v205, v212, v231, s[6:7]
	v_pk_fma_f32 v[206:207], v[138:139], v[206:207], v[142:143]
	v_pk_fma_f32 v[208:209], v[136:137], v[208:209], v[140:141]
	v_pk_fma_f32 v[198:199], v[134:135], v[198:199], v[206:207]
	v_pk_fma_f32 v[204:205], v[132:133], v[204:205], v[208:209]
	v_pk_fma_f32 v[114:115], v[114:115], v[130:131], v[198:199]
	v_pk_fma_f32 v[112:113], v[112:113], v[128:129], v[204:205]
	s_nop 0
	v_mov_b32_e32 v204, v188
	v_mov_b32_e32 v205, v188
	v_pk_mul_f32 v[110:111], v[110:111], v[204:205]
	v_pk_mul_f32 v[108:109], v[108:109], v[188:189]
	s_nop 0
	s_nop 1
	v_mov_b32_dpp v212, v108 row_ror:1 row_mask:0xf bank_mask:0xf
	v_mov_b32_dpp v213, v108 row_ror:2 row_mask:0xf bank_mask:0xf
	v_mov_b32_dpp v214, v109 row_ror:1 row_mask:0xf bank_mask:0xf
	v_mov_b32_dpp v215, v109 row_ror:2 row_mask:0xf bank_mask:0xf
	v_mov_b32_dpp v227, v110 row_ror:1 row_mask:0xf bank_mask:0xf
	v_mov_b32_dpp v228, v110 row_ror:2 row_mask:0xf bank_mask:0xf
	v_mov_b32_dpp v237, v111 row_ror:1 row_mask:0xf bank_mask:0xf
	v_mov_b32_dpp v238, v111 row_ror:2 row_mask:0xf bank_mask:0xf
	s_nop 0
	v_cndmask_b32_e64 v210, v230, v213, s[8:9]
	v_cndmask_b32_e64 v208, v234, v228, s[8:9]
	v_cndmask_b32_e64 v209, v236, v238, s[8:9]
	v_cndmask_b32_e64 v211, v232, v215, s[8:9]
	v_cndmask_b32_e64 v198, v233, v227, s[6:7]
	v_cndmask_b32_e64 v199, v235, v237, s[6:7]
	v_cndmask_b32_e64 v206, v229, v212, s[6:7]
	v_cndmask_b32_e64 v207, v231, v214, s[6:7]
	v_pk_fma_f32 v[208:209], v[138:139], v[208:209], v[142:143]
	v_pk_fma_f32 v[210:211], v[136:137], v[210:211], v[140:141]
	v_pk_fma_f32 v[198:199], v[134:135], v[198:199], v[208:209]
	v_pk_fma_f32 v[206:207], v[132:133], v[206:207], v[210:211]
	v_pk_fma_f32 v[110:111], v[110:111], v[130:131], v[198:199]
	v_pk_fma_f32 v[108:109], v[108:109], v[128:129], v[206:207]
	s_nop 0
	v_mov_b32_e32 v206, v186
	v_mov_b32_e32 v207, v186
	v_pk_mul_f32 v[94:95], v[94:95], v[206:207]
	v_pk_mul_f32 v[92:93], v[92:93], v[186:187]
	s_nop 0
	s_nop 1
	v_mov_b32_dpp v208, v92 row_ror:1 row_mask:0xf bank_mask:0xf
	v_mov_b32_dpp v229, v92 row_ror:2 row_mask:0xf bank_mask:0xf
	v_mov_b32_dpp v209, v93 row_ror:1 row_mask:0xf bank_mask:0xf
	v_mov_b32_dpp v230, v93 row_ror:2 row_mask:0xf bank_mask:0xf
	v_mov_b32_dpp v198, v94 row_ror:1 row_mask:0xf bank_mask:0xf
	v_mov_b32_dpp v210, v94 row_ror:2 row_mask:0xf bank_mask:0xf
	v_mov_b32_dpp v199, v95 row_ror:1 row_mask:0xf bank_mask:0xf
	v_mov_b32_dpp v211, v95 row_ror:2 row_mask:0xf bank_mask:0xf
	s_nop 0
	v_cndmask_b32_e64 v208, v212, v208, s[6:7]
	v_cndmask_b32_e64 v210, v228, v210, s[8:9]
	v_cndmask_b32_e64 v211, v238, v211, s[8:9]
	v_cndmask_b32_e64 v212, v213, v229, s[8:9]
	v_cndmask_b32_e64 v213, v215, v230, s[8:9]
	v_cndmask_b32_e64 v198, v227, v198, s[6:7]
	v_cndmask_b32_e64 v199, v237, v199, s[6:7]
	v_cndmask_b32_e64 v209, v214, v209, s[6:7]
	v_pk_fma_f32 v[138:139], v[138:139], v[210:211], v[142:143]
	v_pk_fma_f32 v[136:137], v[136:137], v[212:213], v[140:141]
	v_pk_fma_f32 v[134:135], v[134:135], v[198:199], v[138:139]
	v_pk_fma_f32 v[132:133], v[132:133], v[208:209], v[136:137]
	v_pk_fma_f32 v[94:95], v[94:95], v[130:131], v[134:135]
	v_pk_fma_f32 v[92:93], v[92:93], v[128:129], v[132:133]
	s_nop 0
	s_movk_i32 s0, 0x5000
	v_add_co_u32_e32 v208, vcc, s0, v164
	v_mov_b32_e32 v198, 0
	s_nop 0
	v_addc_co_u32_e32 v209, vcc, 0, v165, vcc
	v_add_co_u32_e32 v210, vcc, s0, v168
	v_mov_b32_e32 v212, 0
	s_nop 0
	v_addc_co_u32_e32 v211, vcc, 0, v169, vcc
	v_add_co_u32_e32 v136, vcc, 0x5000, v170
	global_load_dwordx4 v[132:135], v[208:209], off offset:2048
	global_load_dwordx4 v[128:131], v[210:211], off offset:2048
	v_addc_co_u32_e32 v137, vcc, 0, v171, vcc
	v_add_co_u32_e32 v140, vcc, 0x5000, v166
	global_load_dwordx4 v[136:139], v[136:137], off offset:2048
	s_nop 0
	v_addc_co_u32_e32 v141, vcc, 0, v167, vcc
	global_load_dwordx4 v[140:143], v[140:141], off offset:2048
	s_and_b64 vcc, exec, s[12:13]
	v_mov_b32_e32 v213, 0
	v_mov_b32_e32 v214, 0
	v_mov_b32_e32 v215, 0
	v_mov_b32_e32 v199, 0
	v_mov_b32_e32 v228, 0
	v_mov_b32_e32 v227, 0
	v_mov_b32_e32 v229, 0
	s_cbranch_vccnz .LBB0_1722
; #define PG8_LAS __attribute__((address_space(3)))
;     __device__ __forceinline__ void operator()(f32x4 (&acc)[2][2][4][2], const Unit& u, int wr, int wc, int fr_, int fq_) const {
;     ...
;                     if (blk) { const f32x4 h14 = *(const PG8_LAS f32x4*)(hal + ((blk - 1) * 2 + 0) * 256 + ct) * rs14, h15 = *(const PG8_LAS f32x4*)(hal + ((blk - 1) * 2 + 1) * 256 + ct) * rs15;
;                         pR1 = h15; pR2 = (fr == 0) ? h14 : h15; }
	ds_read_b128 v[212:215], v226 offset:512
	ds_read_b128 v[228:231], v179 offset:512
	v_mov_b32_e32 v232, v196
	v_mov_b32_e32 v233, v196
	s_waitcnt lgkmcnt(1)
	v_pk_mul_f32 v[234:235], v[196:197], v[212:213]
	v_mov_b32_e32 v212, v194
	v_mov_b32_e32 v213, v194
	v_pk_mul_f32 v[232:233], v[232:233], v[214:215]
	s_waitcnt lgkmcnt(0)
	v_pk_mul_f32 v[214:215], v[212:213], v[230:231]
	v_pk_mul_f32 v[212:213], v[194:195], v[228:229]
	v_cndmask_b32_e64 v227, v214, v232, s[10:11]
	v_cndmask_b32_e64 v229, v215, v233, s[10:11]
	v_cndmask_b32_e64 v199, v212, v234, s[10:11]
	v_cndmask_b32_e64 v228, v213, v235, s[10:11]
; #define PG8_LAS __attribute__((address_space(3)))
; __device__ __forceinline__ float dpp_ror1(float x) { float r; asm volatile("s_nop 1\n\tv_mov_b32_dpp %0, %1 row_ror:1 row_mask:0xf bank_mask:0xf" : "=&v"(r) : "v"(x)); return r; }
; __device__ __forceinline__ float dpp_ror2(float x) { float r; asm volatile("s_nop 1\n\tv_mov_b32_dpp %0, %1 row_ror:2 row_mask:0xf bank_mask:0xf" : "=&v"(r) : "v"(x)); return r; }
;     __device__ __forceinline__ void operator()(f32x4 (&acc)[2][2][4][2], const Unit& u, int wr, int wc, int fr_, int fq_) const {
;     ...
;                 for (int n = 0; n < 2; ++n) {
;                     const int ct = bj * HALF + wc * 32 + 8 * fq + 4 * n;
;                     const int cidx = bj * 5632 + jcol + 4 * n;
;                     const f32x4 w0 = *(const f32x4*)(cw + cidx), w1 = *(const f32x4*)(cw + 11264 + cidx), w2 = *(const f32x4*)(cw + 22528 + cidx), b4 = *(const f32x4*)(cb + cidx);
;                     f32x4 pR1 = (f32x4){0.f, 0.f, 0.f, 0.f}, pR2 = pR1;
;                     if (blk) { const f32x4 h14 = *(const PG8_LAS f32x4*)(hal + ((blk - 1) * 2 + 0) * 256 + ct) * rs14, h15 = *(const PG8_LAS f32x4*)(hal + ((blk - 1) * 2 + 1) * 256 + ct) * rs15;
;                         pR1 = h15; pR2 = (fr == 0) ? h14 : h15; }
; #pragma unroll
;                     for (int m = 0; m < 4; ++m) {
;                         const f32x4 U = acc[ai][bj][m][n] * rsr[m];
;                         f32x4 R1, R2;
; #pragma unroll
;                         for (int i = 0; i < 4; ++i) { R1[i] = dpp_ror1(U[i]); R2[i] = dpp_ror2(U[i]); }
;                         const f32x4 U1 = (fr >= 1) ? R1 : pR1, U2 = (fr >= 2) ? R2 : pR2;
;                         const f32x4 C = b4 + w0 * U2 + w1 * U1 + w2 * U;
;                         acc[ai][bj][m][n] = C; pR1 = R1; pR2 = R2;
.LBB0_1722:
	v_pk_mul_f32 v[102:103], v[102:103], v[200:201]
	v_pk_mul_f32 v[100:101], v[100:101], v[192:193]
	v_cmp_gt_i32_e64 s[0:1], 2, v178
	s_nop 1
	v_mov_b32_dpp v232, v100 row_ror:1 row_mask:0xf bank_mask:0xf
	v_mov_b32_dpp v233, v100 row_ror:2 row_mask:0xf bank_mask:0xf
	v_mov_b32_dpp v234, v101 row_ror:1 row_mask:0xf bank_mask:0xf
	v_mov_b32_dpp v235, v101 row_ror:2 row_mask:0xf bank_mask:0xf
	v_mov_b32_dpp v236, v102 row_ror:1 row_mask:0xf bank_mask:0xf
	v_mov_b32_dpp v237, v102 row_ror:2 row_mask:0xf bank_mask:0xf
	v_mov_b32_dpp v238, v103 row_ror:1 row_mask:0xf bank_mask:0xf
	v_mov_b32_dpp v239, v103 row_ror:2 row_mask:0xf bank_mask:0xf
	s_nop 0
	v_cndmask_b32_e64 v230, v199, v233, s[8:9]
	v_cndmask_b32_e64 v200, v214, v236, s[6:7]
	v_cndmask_b32_e64 v201, v215, v238, s[6:7]
	v_cndmask_b32_e64 v214, v227, v237, s[8:9]
	v_cndmask_b32_e64 v215, v229, v239, s[8:9]
	v_cndmask_b32_e64 v231, v228, v235, s[8:9]
	v_cndmask_b32_e64 v212, v212, v232, s[6:7]
	v_cndmask_b32_e64 v213, v213, v234, s[6:7]
	s_waitcnt vmcnt(0)
	v_pk_fma_f32 v[214:215], v[134:135], v[214:215], v[142:143]
	v_pk_fma_f32 v[228:229], v[132:133], v[230:231], v[140:141]
	v_pk_fma_f32 v[200:201], v[130:131], v[200:201], v[214:215]
	v_pk_fma_f32 v[212:213], v[128:129], v[212:213], v[228:229]
	v_pk_fma_f32 v[102:103], v[102:103], v[138:139], v[200:201]
	v_pk_fma_f32 v[100:101], v[100:101], v[136:137], v[212:213]
	s_nop 0
	v_pk_mul_f32 v[98:99], v[98:99], v[202:203]
	v_pk_mul_f32 v[96:97], v[96:97], v[190:191]
	s_nop 0
	s_nop 1
	v_mov_b32_dpp v199, v96 row_ror:1 row_mask:0xf bank_mask:0xf
	v_mov_b32_dpp v227, v96 row_ror:2 row_mask:0xf bank_mask:0xf
	v_mov_b32_dpp v228, v97 row_ror:1 row_mask:0xf bank_mask:0xf
	v_mov_b32_dpp v229, v97 row_ror:2 row_mask:0xf bank_mask:0xf
	v_mov_b32_dpp v230, v98 row_ror:1 row_mask:0xf bank_mask:0xf
	v_mov_b32_dpp v231, v98 row_ror:2 row_mask:0xf bank_mask:0xf
	v_mov_b32_dpp v240, v99 row_ror:1 row_mask:0xf bank_mask:0xf
	v_mov_b32_dpp v241, v99 row_ror:2 row_mask:0xf bank_mask:0xf
	s_nop 0
	v_cndmask_b32_e64 v214, v233, v227, s[8:9]
	v_cndmask_b32_e64 v212, v237, v231, s[8:9]
	v_cndmask_b32_e64 v213, v239, v241, s[8:9]
	v_cndmask_b32_e64 v215, v235, v229, s[8:9]
	v_cndmask_b32_e64 v200, v236, v230, s[6:7]
	v_cndmask_b32_e64 v201, v238, v240, s[6:7]
	v_cndmask_b32_e64 v202, v232, v199, s[6:7]
	v_cndmask_b32_e64 v203, v234, v228, s[6:7]
	v_pk_fma_f32 v[212:213], v[134:135], v[212:213], v[142:143]
	v_pk_fma_f32 v[214:215], v[132:133], v[214:215], v[140:141]
	v_pk_fma_f32 v[200:201], v[130:131], v[200:201], v[212:213]
	v_pk_fma_f32 v[202:203], v[128:129], v[202:203], v[214:215]
	v_pk_fma_f32 v[98:99], v[98:99], v[138:139], v[200:201]
	v_pk_fma_f32 v[96:97], v[96:97], v[136:137], v[202:203]
	s_nop 0
	v_pk_mul_f32 v[90:91], v[90:91], v[204:205]
	v_pk_mul_f32 v[88:89], v[88:89], v[188:189]
	s_nop 0
	s_nop 1
	v_mov_b32_dpp v214, v88 row_ror:1 row_mask:0xf bank_mask:0xf
	v_mov_b32_dpp v215, v88 row_ror:2 row_mask:0xf bank_mask:0xf
	v_mov_b32_dpp v232, v89 row_ror:1 row_mask:0xf bank_mask:0xf
	v_mov_b32_dpp v233, v89 row_ror:2 row_mask:0xf bank_mask:0xf
	v_mov_b32_dpp v234, v90 row_ror:1 row_mask:0xf bank_mask:0xf
	v_mov_b32_dpp v235, v90 row_ror:2 row_mask:0xf bank_mask:0xf
	v_mov_b32_dpp v236, v91 row_ror:1 row_mask:0xf bank_mask:0xf
	v_mov_b32_dpp v237, v91 row_ror:2 row_mask:0xf bank_mask:0xf
	s_nop 0
	v_cndmask_b32_e64 v212, v227, v215, s[8:9]
	v_cndmask_b32_e64 v204, v231, v235, s[8:9]
	v_cndmask_b32_e64 v205, v241, v237, s[8:9]
	v_cndmask_b32_e64 v213, v229, v233, s[8:9]
	v_cndmask_b32_e64 v200, v230, v234, s[6:7]
	v_cndmask_b32_e64 v201, v240, v236, s[6:7]
	v_cndmask_b32_e64 v202, v199, v214, s[6:7]
	v_cndmask_b32_e64 v203, v228, v232, s[6:7]
	v_pk_fma_f32 v[204:205], v[134:135], v[204:205], v[142:143]
	v_pk_fma_f32 v[212:213], v[132:133], v[212:213], v[140:141]
	v_pk_fma_f32 v[200:201], v[130:131], v[200:201], v[204:205]
	v_pk_fma_f32 v[202:203], v[128:129], v[202:203], v[212:213]
	v_pk_fma_f32 v[90:91], v[90:91], v[138:139], v[200:201]
	v_pk_fma_f32 v[88:89], v[88:89], v[136:137], v[202:203]
	s_nop 0
	v_pk_mul_f32 v[86:87], v[86:87], v[206:207]
	v_pk_mul_f32 v[84:85], v[84:85], v[186:187]
	s_nop 0
	s_nop 1
	v_mov_b32_dpp v199, v84 row_ror:1 row_mask:0xf bank_mask:0xf
	v_mov_b32_dpp v206, v84 row_ror:2 row_mask:0xf bank_mask:0xf
	v_mov_b32_dpp v203, v85 row_ror:1 row_mask:0xf bank_mask:0xf
	v_mov_b32_dpp v207, v85 row_ror:2 row_mask:0xf bank_mask:0xf
	v_mov_b32_dpp v200, v86 row_ror:1 row_mask:0xf bank_mask:0xf
	v_mov_b32_dpp v204, v86 row_ror:2 row_mask:0xf bank_mask:0xf
	v_mov_b32_dpp v201, v87 row_ror:1 row_mask:0xf bank_mask:0xf
	v_mov_b32_dpp v205, v87 row_ror:2 row_mask:0xf bank_mask:0xf
	s_nop 0
	v_cndmask_b32_e64 v206, v215, v206, s[8:9]
	v_cndmask_b32_e64 v204, v235, v204, s[8:9]
	v_cndmask_b32_e64 v205, v237, v205, s[8:9]
	v_cndmask_b32_e64 v207, v233, v207, s[8:9]
	v_cndmask_b32_e64 v200, v234, v200, s[6:7]
	v_cndmask_b32_e64 v201, v236, v201, s[6:7]
	v_cndmask_b32_e64 v202, v214, v199, s[6:7]
	v_cndmask_b32_e64 v203, v232, v203, s[6:7]
	v_pk_fma_f32 v[134:135], v[134:135], v[204:205], v[142:143]
	v_pk_fma_f32 v[132:133], v[132:133], v[206:207], v[140:141]
	v_pk_fma_f32 v[130:131], v[130:131], v[200:201], v[134:135]
	v_pk_fma_f32 v[128:129], v[128:129], v[202:203], v[132:133]
	v_pk_fma_f32 v[86:87], v[86:87], v[138:139], v[130:131]
	v_pk_fma_f32 v[84:85], v[84:85], v[136:137], v[128:129]
	s_nop 0
	v_add_co_u32_e32 v136, vcc, 0x5000, v170
	global_load_dwordx4 v[132:135], v[208:209], off offset:2064
	global_load_dwordx4 v[128:131], v[210:211], off offset:2064
	v_addc_co_u32_e32 v137, vcc, 0, v171, vcc
	v_add_co_u32_e32 v140, vcc, 0x5000, v166
	global_load_dwordx4 v[136:139], v[136:137], off offset:2064
	s_nop 0
	v_addc_co_u32_e32 v141, vcc, 0, v167, vcc
	global_load_dwordx4 v[140:143], v[140:141], off offset:2064
	s_and_b64 vcc, exec, s[12:13]
	s_cbranch_vccnz .LBB0_1724
	ds_read_b128 v[198:201], v226 offset:528
	v_mov_b32_e32 v202, v196
	v_mov_b32_e32 v203, v196
	s_andn2_b64 s[0:1], s[0:1], exec
	s_waitcnt lgkmcnt(0)
	v_pk_mul_f32 v[202:203], v[202:203], v[200:201]
	v_pk_mul_f32 v[204:205], v[196:197], v[198:199]
	ds_read_b128 v[198:201], v179 offset:528
	v_mov_b32_e32 v196, v194
	v_mov_b32_e32 v197, v194
	s_waitcnt lgkmcnt(0)
	v_pk_mul_f32 v[196:197], v[196:197], v[200:201]
	v_pk_mul_f32 v[198:199], v[194:195], v[198:199]
	v_cndmask_b32_e64 v194, v196, v202, s[10:11]
	v_cndmask_b32_e64 v200, v197, v203, s[10:11]
	v_cndmask_b32_e64 v179, v198, v204, s[10:11]
	v_cndmask_b32_e64 v195, v199, v205, s[10:11]
	s_branch .LBB0_1725

; __device__ __forceinline__ float dpp_ror1(float x) { float r; asm volatile("s_nop 1\n\tv_mov_b32_dpp %0, %1 row_ror:1 row_mask:0xf bank_mask:0xf" : "=&v"(r) : "v"(x)); return r; }
; __device__ __forceinline__ float dpp_ror2(float x) { float r; asm volatile("s_nop 1\n\tv_mov_b32_dpp %0, %1 row_ror:2 row_mask:0xf bank_mask:0xf" : "=&v"(r) : "v"(x)); return r; }
;     __device__ __forceinline__ void operator()(f32x4 (&acc)[2][2][4][2], const Unit& u, int wr, int wc, int fr_, int fq_) const {
;     ...
;                     for (int m = 0; m < 4; ++m) {
;                         const f32x4 U = acc[ai][bj][m][n] * rsr[m];
;                         f32x4 R1, R2;
; #pragma unroll
;                         for (int i = 0; i < 4; ++i) { R1[i] = dpp_ror1(U[i]); R2[i] = dpp_ror2(U[i]); }
;                         const f32x4 U1 = (fr >= 1) ? R1 : pR1, U2 = (fr >= 2) ? R2 : pR2;
;                         const f32x4 C = b4 + w0 * U2 + w1 * U1 + w2 * U;
;                         acc[ai][bj][m][n] = C; pR1 = R1; pR2 = R2;
;                         asm volatile("" : "+v"(acc[ai][bj][m][n]));
;                         __builtin_amdgcn_sched_barrier(0);
;                     }
;                     asm volatile("" ::: "memory");
;                 }
;             if (ai == 0 && wr == 0 && fr < 2) {
; #pragma unroll
;                 for (int bj = 0; bj < 2; ++bj)
; #pragma unroll
;                     for (int n = 0; n < 2; ++n) *(f32x4*)(TOP + ((size_t)u.pm * 2 + fr) * 11264 + u.pn * BM + bj * HALF + wc * 32 + 8 * fq + 4 * n) = acc[0][bj][0][n]; }
.LBB0_1725:
	v_mov_b32_e32 v202, v192
	v_mov_b32_e32 v203, v192
	v_pk_mul_f32 v[78:79], v[78:79], v[202:203]
	v_pk_mul_f32 v[76:77], v[76:77], v[192:193]
	s_nop 0
	s_nop 1
	v_mov_b32_dpp v201, v76 row_ror:1 row_mask:0xf bank_mask:0xf
	v_mov_b32_dpp v202, v76 row_ror:2 row_mask:0xf bank_mask:0xf
	v_mov_b32_dpp v203, v77 row_ror:1 row_mask:0xf bank_mask:0xf
	v_mov_b32_dpp v204, v77 row_ror:2 row_mask:0xf bank_mask:0xf
	v_mov_b32_dpp v205, v78 row_ror:1 row_mask:0xf bank_mask:0xf
	v_mov_b32_dpp v206, v78 row_ror:2 row_mask:0xf bank_mask:0xf
	v_mov_b32_dpp v207, v79 row_ror:1 row_mask:0xf bank_mask:0xf
	v_mov_b32_dpp v208, v79 row_ror:2 row_mask:0xf bank_mask:0xf
	s_nop 0
	v_cndmask_b32_e64 v192, v196, v205, s[6:7]
	v_cndmask_b32_e64 v193, v197, v207, s[6:7]
	v_cndmask_b32_e64 v196, v198, v201, s[6:7]
	v_cndmask_b32_e64 v197, v199, v203, s[6:7]
	v_cndmask_b32_e64 v198, v194, v206, s[8:9]
	v_cndmask_b32_e64 v199, v200, v208, s[8:9]
	v_cndmask_b32_e64 v194, v179, v202, s[8:9]
	v_cndmask_b32_e64 v195, v195, v204, s[8:9]
	s_waitcnt vmcnt(0)
	v_pk_fma_f32 v[198:199], v[134:135], v[198:199], v[142:143]
	v_pk_fma_f32 v[194:195], v[132:133], v[194:195], v[140:141]
	v_pk_fma_f32 v[192:193], v[130:131], v[192:193], v[198:199]
	v_pk_fma_f32 v[194:195], v[128:129], v[196:197], v[194:195]
	v_pk_fma_f32 v[78:79], v[78:79], v[138:139], v[192:193]
	v_pk_fma_f32 v[76:77], v[76:77], v[136:137], v[194:195]
	s_nop 0
	v_mov_b32_e32 v192, v190
	v_mov_b32_e32 v193, v190
	v_pk_mul_f32 v[74:75], v[74:75], v[192:193]
	v_pk_mul_f32 v[72:73], v[72:73], v[190:191]
	s_nop 0
	s_nop 1
	v_mov_b32_dpp v179, v72 row_ror:1 row_mask:0xf bank_mask:0xf
	v_mov_b32_dpp v198, v72 row_ror:2 row_mask:0xf bank_mask:0xf
	v_mov_b32_dpp v199, v73 row_ror:1 row_mask:0xf bank_mask:0xf
	v_mov_b32_dpp v200, v73 row_ror:2 row_mask:0xf bank_mask:0xf
	v_mov_b32_dpp v209, v74 row_ror:1 row_mask:0xf bank_mask:0xf
	v_mov_b32_dpp v210, v74 row_ror:2 row_mask:0xf bank_mask:0xf
	v_mov_b32_dpp v211, v75 row_ror:1 row_mask:0xf bank_mask:0xf
	v_mov_b32_dpp v212, v75 row_ror:2 row_mask:0xf bank_mask:0xf
	s_nop 0
	v_cndmask_b32_e64 v196, v202, v198, s[8:9]
	v_cndmask_b32_e64 v194, v206, v210, s[8:9]
	v_cndmask_b32_e64 v195, v208, v212, s[8:9]
	v_cndmask_b32_e64 v197, v204, v200, s[8:9]
	v_cndmask_b32_e64 v190, v205, v209, s[6:7]
	v_cndmask_b32_e64 v191, v207, v211, s[6:7]
	v_cndmask_b32_e64 v192, v201, v179, s[6:7]
	v_cndmask_b32_e64 v193, v203, v199, s[6:7]
	v_pk_fma_f32 v[194:195], v[134:135], v[194:195], v[142:143]
	v_pk_fma_f32 v[196:197], v[132:133], v[196:197], v[140:141]
	v_pk_fma_f32 v[190:191], v[130:131], v[190:191], v[194:195]
	v_pk_fma_f32 v[192:193], v[128:129], v[192:193], v[196:197]
	v_pk_fma_f32 v[74:75], v[74:75], v[138:139], v[190:191]
	v_pk_fma_f32 v[72:73], v[72:73], v[136:137], v[192:193]
	s_nop 0
	v_mov_b32_e32 v190, v188
	v_mov_b32_e32 v191, v188
	v_pk_mul_f32 v[70:71], v[70:71], v[190:191]
	v_pk_mul_f32 v[68:69], v[68:69], v[188:189]
	s_nop 0
	s_nop 1
	v_mov_b32_dpp v196, v68 row_ror:1 row_mask:0xf bank_mask:0xf
	v_mov_b32_dpp v197, v68 row_ror:2 row_mask:0xf bank_mask:0xf
	v_mov_b32_dpp v201, v69 row_ror:1 row_mask:0xf bank_mask:0xf
	v_mov_b32_dpp v202, v69 row_ror:2 row_mask:0xf bank_mask:0xf
	v_mov_b32_dpp v203, v70 row_ror:1 row_mask:0xf bank_mask:0xf
	v_mov_b32_dpp v204, v70 row_ror:2 row_mask:0xf bank_mask:0xf
	v_mov_b32_dpp v205, v71 row_ror:1 row_mask:0xf bank_mask:0xf
	v_mov_b32_dpp v206, v71 row_ror:2 row_mask:0xf bank_mask:0xf
	s_nop 0
	v_cndmask_b32_e64 v194, v198, v197, s[8:9]
	v_cndmask_b32_e64 v192, v210, v204, s[8:9]
	v_cndmask_b32_e64 v193, v212, v206, s[8:9]
	v_cndmask_b32_e64 v195, v200, v202, s[8:9]
	v_cndmask_b32_e64 v188, v209, v203, s[6:7]
	v_cndmask_b32_e64 v189, v211, v205, s[6:7]
	v_cndmask_b32_e64 v190, v179, v196, s[6:7]
	v_cndmask_b32_e64 v191, v199, v201, s[6:7]
	v_pk_fma_f32 v[192:193], v[134:135], v[192:193], v[142:143]
	v_pk_fma_f32 v[194:195], v[132:133], v[194:195], v[140:141]
	v_pk_fma_f32 v[188:189], v[130:131], v[188:189], v[192:193]
	v_pk_fma_f32 v[190:191], v[128:129], v[190:191], v[194:195]
	v_pk_fma_f32 v[70:71], v[70:71], v[138:139], v[188:189]
	v_pk_fma_f32 v[68:69], v[68:69], v[136:137], v[190:191]
	s_nop 0
	v_mov_b32_e32 v188, v186
	v_mov_b32_e32 v189, v186
	v_pk_mul_f32 v[66:67], v[66:67], v[188:189]
	v_pk_mul_f32 v[64:65], v[64:65], v[186:187]
	s_nop 0
	s_nop 1
	v_mov_b32_dpp v179, v64 row_ror:1 row_mask:0xf bank_mask:0xf
	v_mov_b32_dpp v192, v64 row_ror:2 row_mask:0xf bank_mask:0xf
	v_mov_b32_dpp v189, v65 row_ror:1 row_mask:0xf bank_mask:0xf
	v_mov_b32_dpp v193, v65 row_ror:2 row_mask:0xf bank_mask:0xf
	v_mov_b32_dpp v186, v66 row_ror:1 row_mask:0xf bank_mask:0xf
	v_mov_b32_dpp v190, v66 row_ror:2 row_mask:0xf bank_mask:0xf
	v_mov_b32_dpp v187, v67 row_ror:1 row_mask:0xf bank_mask:0xf
	v_mov_b32_dpp v191, v67 row_ror:2 row_mask:0xf bank_mask:0xf
	s_nop 0
	v_cndmask_b32_e64 v192, v197, v192, s[8:9]
	v_cndmask_b32_e64 v190, v204, v190, s[8:9]
	v_cndmask_b32_e64 v191, v206, v191, s[8:9]
	v_cndmask_b32_e64 v193, v202, v193, s[8:9]
	v_cndmask_b32_e64 v186, v203, v186, s[6:7]
	v_cndmask_b32_e64 v187, v205, v187, s[6:7]
	v_cndmask_b32_e64 v188, v196, v179, s[6:7]
	v_cndmask_b32_e64 v189, v201, v189, s[6:7]
	v_pk_fma_f32 v[134:135], v[134:135], v[190:191], v[142:143]
	v_pk_fma_f32 v[132:133], v[132:133], v[192:193], v[140:141]
	v_pk_fma_f32 v[130:131], v[130:131], v[186:187], v[134:135]
	v_pk_fma_f32 v[128:129], v[128:129], v[188:189], v[132:133]
	v_pk_fma_f32 v[66:67], v[66:67], v[138:139], v[130:131]
	v_pk_fma_f32 v[64:65], v[64:65], v[136:137], v[128:129]
	s_nop 0
	s_and_saveexec_b64 s[12:13], s[0:1]
	s_cbranch_execz .LBB0_1727
	v_readlane_b32 s0, v244, 49
	v_ashrrev_i32_e32 v179, 31, v178
	v_readlane_b32 s1, v244, 50
	v_lshl_add_u64 v[128:129], v[184:185], 0, v[178:179]
	s_mov_b32 s16, 0xb000
	v_mov_b64_e32 v[130:131], s[0:1]
	v_mad_u64_u32 v[130:131], s[0:1], v128, s16, v[130:131]
	v_mov_b32_e32 v128, v131
	v_mad_u64_u32 v[128:129], s[0:1], v129, s16, v[128:129]
	v_mov_b32_e32 v131, v128
	v_lshl_add_u64 v[128:129], v[182:183], 2, v[130:131]
	s_lshl_b32 s16, s33, 2
	v_lshl_add_u64 v[128:129], v[128:129], 0, s[16:17]
	v_lshl_add_u64 v[128:129], v[176:177], 2, v[128:129]
	global_store_dwordx4 v[128:129], v[124:127], off
	global_store_dwordx4 v[128:129], v[116:119], off offset:16
	global_store_dwordx4 v[128:129], v[100:103], off offset:512
	global_store_dwordx4 v[128:129], v[76:79], off offset:528
; __device__ __forceinline__ u32x4 pack8(f32x4 v0, f32x4 v1) { u32x4 w; w.x = cvt_pk_bf16(v0[0], v0[1]); w.y = cvt_pk_bf16(v0[2], v0[3]); w.z = cvt_pk_bf16(v1[0], v1[1]); w.w = cvt_pk_bf16(v1[2], v1[3]); return w; }
; __device__ __forceinline__ f32x4 gelu4(f32x4 v) { f32x2 a = gelu_pk((f32x2){v[0], v[1]}), b = gelu_pk((f32x2){v[2], v[3]}); return (f32x4){a.x, a.y, b.x, b.y}; }
; __device__ __forceinline__ f32x2 gelu_pk(f32x2 v) {
;     const f32x2 av = __builtin_elementwise_abs(v), d = av * 0.2316418882f + 1.0f;
;     f32x2 t; t.x = __builtin_amdgcn_rcpf(d.x); t.y = __builtin_amdgcn_rcpf(d.y);
;     f32x2 q = t * 0.5307027145f + (-0.7265760135f); q = q * t + 0.7107068705f; q = q * t + (-0.142248368f); q = q * t + 0.127414796f; q = q * t;
;     const f32x2 s = (v * v) * (-0.72134752044f);
;     f32x2 e; e.x = __builtin_amdgcn_exp2f(s.x); e.y = __builtin_amdgcn_exp2f(s.y);
;     const f32x2 m = v * (q * e), r = v - m;
;     f32x2 o; o.x = v.x < 0.f ? m.x : r.x; o.y = v.y < 0.f ? m.y : r.y; return o;
; }
;     __device__ __forceinline__ void operator()(f32x4 (&acc)[2][2][4][2], const Unit& u, int wr, int wc, int fr_, int fq_) const {
;     ...
;             for (int m = 0; m < 4; ++m) { const int row = u.pm * BM + blk * 64 + m * 16 + fr;
;                 const f32x4 g0 = gelu4(acc[ai][0][m][0]), g1 = gelu4(acc[ai][0][m][1]);
;                 *(u32x4*)(ACT + (size_t)row * 5632 + jcol) = pack8(g0 * acc[ai][1][m][0], g1 * acc[ai][1][m][1]); asm volatile("" ::: "memory"); __builtin_amdgcn_sched_barrier(0); }
.LBB0_1727:
	s_or_b64 exec, exec, s[12:13]
	v_and_b32_e32 v129, 0x7fffffff, v125
	v_and_b32_e32 v128, 0x7fffffff, v124
	v_pk_fma_f32 v[128:129], v[128:129], s[58:59], 1.0 op_sel_hi:[1,0,0]
	v_lshl_add_u32 v178, s90, 8, v178
	v_rcp_f32_e32 v182, v128
	v_rcp_f32_e32 v183, v129
	v_readlane_b32 s0, v244, 55
	v_pk_mul_f32 v[186:187], v[124:125], v[124:125]
	v_cmp_gt_f32_e32 vcc, 0, v124
	v_add_u32_e32 v179, s0, v178
	s_mov_b32 s0, 0xbf3a00e3
	v_mov_b64_e32 v[128:129], s[0:1]
	v_pk_fma_f32 v[184:185], v[182:183], s[60:61], v[128:129] op_sel_hi:[1,0,0]
	v_pk_mul_f32 v[186:187], v[186:187], s[50:51] op_sel_hi:[1,0]
	v_pk_fma_f32 v[184:185], v[182:183], v[184:185], s[62:63] op_sel_hi:[1,1,0]
	v_exp_f32_e32 v186, v186
	v_exp_f32_e32 v187, v187
	v_pk_fma_f32 v[184:185], v[182:183], v[184:185], s[64:65] op_sel_hi:[1,1,0]
	v_lshl_add_u64 v[138:139], v[164:165], 0, s[54:55]
	v_pk_fma_f32 v[184:185], v[182:183], v[184:185], s[66:67] op_sel_hi:[1,1,0]
	v_lshl_add_u64 v[140:141], v[168:169], 0, s[54:55]
	v_pk_mul_f32 v[182:183], v[182:183], v[184:185]
	v_pk_mul_f32 v[184:185], v[126:127], v[126:127]
	v_pk_mul_f32 v[182:183], v[186:187], v[182:183]
	v_pk_mul_f32 v[184:185], v[184:185], s[50:51] op_sel_hi:[1,0]
	v_pk_mul_f32 v[186:187], v[124:125], v[182:183]
	v_pk_fma_f32 v[182:183], v[124:125], v[182:183], v[124:125] neg_lo:[1,0,0] neg_hi:[1,0,0]
	v_exp_f32_e32 v184, v184
	v_cndmask_b32_e32 v124, v182, v186, vcc
	v_cmp_gt_f32_e32 vcc, 0, v125
	v_and_b32_e32 v182, 0x7fffffff, v126
	v_exp_f32_e32 v185, v185
	v_cndmask_b32_e32 v125, v183, v187, vcc
	v_and_b32_e32 v183, 0x7fffffff, v127
	v_pk_fma_f32 v[182:183], v[182:183], s[58:59], 1.0 op_sel_hi:[1,0,0]
	v_cmp_gt_f32_e32 vcc, 0, v126
	v_rcp_f32_e32 v182, v182
	v_rcp_f32_e32 v183, v183
	v_pk_mul_f32 v[100:101], v[124:125], v[100:101]
	v_lshl_add_u64 v[142:143], v[170:171], 0, s[54:55]
	v_cvt_pk_bf16_f32 v100, v100, v101
	v_pk_fma_f32 v[186:187], v[182:183], s[60:61], v[128:129] op_sel_hi:[1,0,0]
	v_lshl_add_u64 v[176:177], v[166:167], 0, s[54:55]
	v_pk_fma_f32 v[186:187], v[182:183], v[186:187], s[62:63] op_sel_hi:[1,1,0]
	v_lshl_add_u64 v[130:131], v[164:165], 0, s[56:57]
	v_pk_fma_f32 v[186:187], v[182:183], v[186:187], s[64:65] op_sel_hi:[1,1,0]
	v_lshl_add_u64 v[132:133], v[168:169], 0, s[56:57]
	v_pk_fma_f32 v[186:187], v[182:183], v[186:187], s[66:67] op_sel_hi:[1,1,0]
	v_lshl_add_u64 v[134:135], v[170:171], 0, s[56:57]
	v_pk_mul_f32 v[182:183], v[182:183], v[186:187]
	v_pk_mul_f32 v[186:187], v[116:117], v[116:117]
	v_pk_mul_f32 v[182:183], v[184:185], v[182:183]
	v_pk_mul_f32 v[186:187], v[186:187], s[50:51] op_sel_hi:[1,0]
	v_pk_mul_f32 v[184:185], v[126:127], v[182:183]
	v_pk_fma_f32 v[182:183], v[126:127], v[182:183], v[126:127] neg_lo:[1,0,0] neg_hi:[1,0,0]
	v_exp_f32_e32 v186, v186
	v_cndmask_b32_e32 v126, v182, v184, vcc
	v_cmp_gt_f32_e32 vcc, 0, v127
	v_and_b32_e32 v182, 0x7fffffff, v116
	v_exp_f32_e32 v187, v187
	v_cndmask_b32_e32 v127, v183, v185, vcc
	v_and_b32_e32 v183, 0x7fffffff, v117
	v_pk_fma_f32 v[182:183], v[182:183], s[58:59], 1.0 op_sel_hi:[1,0,0]
	v_cmp_gt_f32_e32 vcc, 0, v116
	v_rcp_f32_e32 v182, v182
	v_rcp_f32_e32 v183, v183
	v_pk_mul_f32 v[102:103], v[126:127], v[102:103]
	v_lshl_add_u64 v[136:137], v[166:167], 0, s[56:57]
	v_cvt_pk_bf16_f32 v101, v102, v103
	v_pk_fma_f32 v[184:185], v[182:183], s[60:61], v[128:129] op_sel_hi:[1,0,0]
	s_nop 0
	v_pk_fma_f32 v[184:185], v[182:183], v[184:185], s[62:63] op_sel_hi:[1,1,0]
	s_nop 0
	v_pk_fma_f32 v[184:185], v[182:183], v[184:185], s[64:65] op_sel_hi:[1,1,0]
	s_nop 0
	v_pk_fma_f32 v[184:185], v[182:183], v[184:185], s[66:67] op_sel_hi:[1,1,0]
	s_nop 0
	v_pk_mul_f32 v[182:183], v[182:183], v[184:185]
	v_pk_mul_f32 v[184:185], v[118:119], v[118:119]
	v_pk_mul_f32 v[182:183], v[186:187], v[182:183]
	v_pk_mul_f32 v[184:185], v[184:185], s[50:51] op_sel_hi:[1,0]
	v_pk_mul_f32 v[186:187], v[116:117], v[182:183]
	v_pk_fma_f32 v[182:183], v[116:117], v[182:183], v[116:117] neg_lo:[1,0,0] neg_hi:[1,0,0]
	v_exp_f32_e32 v184, v184
	v_cndmask_b32_e32 v116, v182, v186, vcc
	v_cmp_gt_f32_e32 vcc, 0, v117
	v_and_b32_e32 v182, 0x7fffffff, v118
	v_exp_f32_e32 v185, v185
	v_cndmask_b32_e32 v117, v183, v187, vcc
	v_and_b32_e32 v183, 0x7fffffff, v119
	v_pk_fma_f32 v[182:183], v[182:183], s[58:59], 1.0 op_sel_hi:[1,0,0]
	v_cmp_gt_f32_e32 vcc, 0, v118
	v_rcp_f32_e32 v182, v182
	v_rcp_f32_e32 v183, v183
	v_pk_mul_f32 v[76:77], v[116:117], v[76:77]
	v_pk_fma_f32 v[186:187], v[182:183], s[60:61], v[128:129] op_sel_hi:[1,0,0]
	s_nop 0
	v_pk_fma_f32 v[186:187], v[182:183], v[186:187], s[62:63] op_sel_hi:[1,1,0]
	v_cvt_pk_bf16_f32 v102, v76, v77
	v_pk_fma_f32 v[186:187], v[182:183], v[186:187], s[64:65] op_sel_hi:[1,1,0]
	v_mov_b64_e32 v[76:77], s[22:23]
	v_pk_fma_f32 v[186:187], v[182:183], v[186:187], s[66:67] op_sel_hi:[1,1,0]
	v_mad_i64_i32 v[116:117], s[0:1], v179, s93, v[76:77]
	v_pk_mul_f32 v[182:183], v[182:183], v[186:187]
	s_nop 0
	v_pk_mul_f32 v[182:183], v[184:185], v[182:183]
	s_nop 0
	v_pk_mul_f32 v[184:185], v[118:119], v[182:183]
	v_pk_fma_f32 v[182:183], v[118:119], v[182:183], v[118:119] neg_lo:[1,0,0] neg_hi:[1,0,0]
	s_nop 0
	v_cndmask_b32_e32 v118, v182, v184, vcc
	v_cmp_gt_f32_e32 vcc, 0, v119
	s_nop 1
	v_cndmask_b32_e32 v119, v183, v185, vcc
	v_pk_mul_f32 v[78:79], v[118:119], v[78:79]
	s_nop 0
	v_cvt_pk_bf16_f32 v103, v78, v79
	v_lshlrev_b64 v[78:79], 1, v[180:181]
	v_lshl_add_u64 v[116:117], v[116:117], 0, v[78:79]
	global_store_dwordx4 v[116:117], v[100:103], off
	s_nop 1
	v_and_b32_e32 v101, 0x7fffffff, v121
	v_and_b32_e32 v100, 0x7fffffff, v120
	v_pk_fma_f32 v[100:101], v[100:101], s[58:59], 1.0 op_sel_hi:[1,0,0]
; __device__ __forceinline__ u32x4 pack8(f32x4 v0, f32x4 v1) { u32x4 w; w.x = cvt_pk_bf16(v0[0], v0[1]); w.y = cvt_pk_bf16(v0[2], v0[3]); w.z = cvt_pk_bf16(v1[0], v1[1]); w.w = cvt_pk_bf16(v1[2], v1[3]); return w; }
; __device__ __forceinline__ f32x4 gelu4(f32x4 v) { f32x2 a = gelu_pk((f32x2){v[0], v[1]}), b = gelu_pk((f32x2){v[2], v[3]}); return (f32x4){a.x, a.y, b.x, b.y}; }
; __device__ __forceinline__ f32x2 gelu_pk(f32x2 v) {
;     const f32x2 av = __builtin_elementwise_abs(v), d = av * 0.2316418882f + 1.0f;
;     f32x2 t; t.x = __builtin_amdgcn_rcpf(d.x); t.y = __builtin_amdgcn_rcpf(d.y);
;     f32x2 q = t * 0.5307027145f + (-0.7265760135f); q = q * t + 0.7107068705f; q = q * t + (-0.142248368f); q = q * t + 0.127414796f; q = q * t;
;     const f32x2 s = (v * v) * (-0.72134752044f);
;     f32x2 e; e.x = __builtin_amdgcn_exp2f(s.x); e.y = __builtin_amdgcn_exp2f(s.y);
;     const f32x2 m = v * (q * e), r = v - m;
;     f32x2 o; o.x = v.x < 0.f ? m.x : r.x; o.y = v.y < 0.f ? m.y : r.y; return o;
; }
;     __device__ __forceinline__ void operator()(f32x4 (&acc)[2][2][4][2], const Unit& u, int wr, int wc, int fr_, int fq_) const {
;     ...
;             for (int m = 0; m < 4; ++m) { const int row = u.pm * BM + blk * 64 + m * 16 + fr;
;                 const f32x4 g0 = gelu4(acc[ai][0][m][0]), g1 = gelu4(acc[ai][0][m][1]);
;                 *(u32x4*)(ACT + (size_t)row * 5632 + jcol) = pack8(g0 * acc[ai][1][m][0], g1 * acc[ai][1][m][1]); asm volatile("" ::: "memory"); __builtin_amdgcn_sched_barrier(0); }
	v_pk_mul_f32 v[116:117], v[120:121], v[120:121]
	v_rcp_f32_e32 v100, v100
	v_rcp_f32_e32 v101, v101
	v_pk_mul_f32 v[116:117], v[116:117], s[50:51] op_sel_hi:[1,0]
	v_cmp_gt_f32_e32 vcc, 0, v120
	v_exp_f32_e32 v116, v116
	v_pk_fma_f32 v[102:103], v[100:101], s[60:61], v[128:129] op_sel_hi:[1,0,0]
	v_exp_f32_e32 v117, v117
	v_pk_fma_f32 v[102:103], v[100:101], v[102:103], s[62:63] op_sel_hi:[1,1,0]
	v_add_u32_e32 v124, 16, v179
	v_pk_fma_f32 v[102:103], v[100:101], v[102:103], s[64:65] op_sel_hi:[1,1,0]
	s_nop 0
	v_pk_fma_f32 v[102:103], v[100:101], v[102:103], s[66:67] op_sel_hi:[1,1,0]
	s_nop 0
	v_pk_mul_f32 v[100:101], v[100:101], v[102:103]
	v_pk_mul_f32 v[102:103], v[122:123], v[122:123]
	v_pk_mul_f32 v[100:101], v[116:117], v[100:101]
	v_pk_mul_f32 v[102:103], v[102:103], s[50:51] op_sel_hi:[1,0]
	v_pk_mul_f32 v[116:117], v[120:121], v[100:101]
	v_pk_fma_f32 v[100:101], v[120:121], v[100:101], v[120:121] neg_lo:[1,0,0] neg_hi:[1,0,0]
	v_exp_f32_e32 v102, v102
	v_cndmask_b32_e32 v100, v100, v116, vcc
	v_cmp_gt_f32_e32 vcc, 0, v121
	v_and_b32_e32 v116, 0x7fffffff, v122
	v_exp_f32_e32 v103, v103
	v_cndmask_b32_e32 v101, v101, v117, vcc
	v_and_b32_e32 v117, 0x7fffffff, v123
	v_pk_fma_f32 v[116:117], v[116:117], s[58:59], 1.0 op_sel_hi:[1,0,0]
	v_cmp_gt_f32_e32 vcc, 0, v122
	v_rcp_f32_e32 v116, v116
	v_rcp_f32_e32 v117, v117
	v_pk_mul_f32 v[120:121], v[112:113], v[112:113]
	v_pk_mul_f32 v[96:97], v[100:101], v[96:97]
	v_pk_mul_f32 v[120:121], v[120:121], s[50:51] op_sel_hi:[1,0]
	v_pk_fma_f32 v[118:119], v[116:117], s[60:61], v[128:129] op_sel_hi:[1,0,0]
	v_exp_f32_e32 v120, v120
	v_pk_fma_f32 v[118:119], v[116:117], v[118:119], s[62:63] op_sel_hi:[1,1,0]
	v_exp_f32_e32 v121, v121
	v_pk_fma_f32 v[118:119], v[116:117], v[118:119], s[64:65] op_sel_hi:[1,1,0]
	s_nop 0
	v_pk_fma_f32 v[118:119], v[116:117], v[118:119], s[66:67] op_sel_hi:[1,1,0]
	s_nop 0
	v_pk_mul_f32 v[116:117], v[116:117], v[118:119]
	s_nop 0
	v_pk_mul_f32 v[102:103], v[102:103], v[116:117]
	s_nop 0
	v_pk_mul_f32 v[116:117], v[122:123], v[102:103]
	v_pk_fma_f32 v[102:103], v[122:123], v[102:103], v[122:123] neg_lo:[1,0,0] neg_hi:[1,0,0]
	s_nop 0
	v_cndmask_b32_e32 v102, v102, v116, vcc
	v_cmp_gt_f32_e32 vcc, 0, v123
	v_and_b32_e32 v116, 0x7fffffff, v112
	s_nop 0
	v_cndmask_b32_e32 v103, v103, v117, vcc
	v_and_b32_e32 v117, 0x7fffffff, v113
	v_pk_fma_f32 v[116:117], v[116:117], s[58:59], 1.0 op_sel_hi:[1,0,0]
	v_cmp_gt_f32_e32 vcc, 0, v112
	v_rcp_f32_e32 v116, v116
	v_rcp_f32_e32 v117, v117
	v_pk_mul_f32 v[98:99], v[102:103], v[98:99]
	v_pk_fma_f32 v[118:119], v[116:117], s[60:61], v[128:129] op_sel_hi:[1,0,0]
	s_nop 0
	v_pk_fma_f32 v[118:119], v[116:117], v[118:119], s[62:63] op_sel_hi:[1,1,0]
	s_nop 0
	v_pk_fma_f32 v[118:119], v[116:117], v[118:119], s[64:65] op_sel_hi:[1,1,0]
	s_nop 0
	v_pk_fma_f32 v[118:119], v[116:117], v[118:119], s[66:67] op_sel_hi:[1,1,0]
	s_nop 0
	v_pk_mul_f32 v[116:117], v[116:117], v[118:119]
	v_pk_mul_f32 v[118:119], v[114:115], v[114:115]
	v_pk_mul_f32 v[116:117], v[120:121], v[116:117]
	v_pk_mul_f32 v[118:119], v[118:119], s[50:51] op_sel_hi:[1,0]
	v_pk_mul_f32 v[120:121], v[112:113], v[116:117]
	v_pk_fma_f32 v[116:117], v[112:113], v[116:117], v[112:113] neg_lo:[1,0,0] neg_hi:[1,0,0]
	v_exp_f32_e32 v118, v118
	v_cndmask_b32_e32 v112, v116, v120, vcc
	v_cmp_gt_f32_e32 vcc, 0, v113
	v_and_b32_e32 v116, 0x7fffffff, v114
	v_exp_f32_e32 v119, v119
	v_cndmask_b32_e32 v113, v117, v121, vcc
	v_and_b32_e32 v117, 0x7fffffff, v115
	v_pk_fma_f32 v[116:117], v[116:117], s[58:59], 1.0 op_sel_hi:[1,0,0]
	v_cmp_gt_f32_e32 vcc, 0, v114
	v_rcp_f32_e32 v116, v116
	v_rcp_f32_e32 v117, v117
	s_nop 0
	v_pk_fma_f32 v[120:121], v[116:117], s[60:61], v[128:129] op_sel_hi:[1,0,0]
	s_nop 0
	v_pk_fma_f32 v[120:121], v[116:117], v[120:121], s[62:63] op_sel_hi:[1,1,0]
	s_nop 0
	v_pk_fma_f32 v[120:121], v[116:117], v[120:121], s[64:65] op_sel_hi:[1,1,0]
	s_nop 0
	v_pk_fma_f32 v[120:121], v[116:117], v[120:121], s[66:67] op_sel_hi:[1,1,0]
	s_nop 0
	v_pk_mul_f32 v[116:117], v[116:117], v[120:121]
	s_nop 0
	v_pk_mul_f32 v[116:117], v[118:119], v[116:117]
	s_nop 0
	v_pk_mul_f32 v[118:119], v[114:115], v[116:117]
	v_pk_fma_f32 v[116:117], v[114:115], v[116:117], v[114:115] neg_lo:[1,0,0] neg_hi:[1,0,0]
	s_nop 0
	v_cndmask_b32_e32 v114, v116, v118, vcc
	v_cmp_gt_f32_e32 vcc, 0, v115
	s_nop 1
	v_cndmask_b32_e32 v115, v117, v119, vcc
	v_pk_mul_f32 v[100:101], v[114:115], v[74:75]
	v_pk_mul_f32 v[74:75], v[112:113], v[72:73]
	v_cvt_pk_bf16_f32 v72, v96, v97
	v_mad_i64_i32 v[96:97], s[0:1], v124, s93, v[76:77]
	v_cvt_pk_bf16_f32 v73, v98, v99
	v_cvt_pk_bf16_f32 v74, v74, v75
	v_cvt_pk_bf16_f32 v75, v100, v101
	v_lshl_add_u64 v[96:97], v[96:97], 0, v[78:79]
	global_store_dwordx4 v[96:97], v[72:75], off
	s_nop 1
	v_and_b32_e32 v73, 0x7fffffff, v105
	v_and_b32_e32 v72, 0x7fffffff, v104
	v_pk_fma_f32 v[72:73], v[72:73], s[58:59], 1.0 op_sel_hi:[1,0,0]
	v_pk_mul_f32 v[96:97], v[104:105], v[104:105]
	v_rcp_f32_e32 v72, v72
	v_rcp_f32_e32 v73, v73
	v_pk_mul_f32 v[96:97], v[96:97], s[50:51] op_sel_hi:[1,0]
	v_cmp_gt_f32_e32 vcc, 0, v104
	v_exp_f32_e32 v96, v96
	v_pk_fma_f32 v[74:75], v[72:73], s[60:61], v[128:129] op_sel_hi:[1,0,0]
	v_exp_f32_e32 v97, v97
	v_pk_fma_f32 v[74:75], v[72:73], v[74:75], s[62:63] op_sel_hi:[1,1,0]
	v_pk_mul_f32 v[100:101], v[108:109], v[108:109]
	v_pk_fma_f32 v[74:75], v[72:73], v[74:75], s[64:65] op_sel_hi:[1,1,0]
	v_pk_mul_f32 v[100:101], v[100:101], s[50:51] op_sel_hi:[1,0]
	v_pk_fma_f32 v[74:75], v[72:73], v[74:75], s[66:67] op_sel_hi:[1,1,0]
	v_exp_f32_e32 v100, v100
	v_pk_mul_f32 v[72:73], v[72:73], v[74:75]
	v_pk_mul_f32 v[74:75], v[106:107], v[106:107]
; __device__ __forceinline__ u32x4 pack8(f32x4 v0, f32x4 v1) { u32x4 w; w.x = cvt_pk_bf16(v0[0], v0[1]); w.y = cvt_pk_bf16(v0[2], v0[3]); w.z = cvt_pk_bf16(v1[0], v1[1]); w.w = cvt_pk_bf16(v1[2], v1[3]); return w; }
; __device__ __forceinline__ f32x4 gelu4(f32x4 v) { f32x2 a = gelu_pk((f32x2){v[0], v[1]}), b = gelu_pk((f32x2){v[2], v[3]}); return (f32x4){a.x, a.y, b.x, b.y}; }
; __device__ __forceinline__ f32x2 gelu_pk(f32x2 v) {
;     const f32x2 av = __builtin_elementwise_abs(v), d = av * 0.2316418882f + 1.0f;
;     f32x2 t; t.x = __builtin_amdgcn_rcpf(d.x); t.y = __builtin_amdgcn_rcpf(d.y);
;     f32x2 q = t * 0.5307027145f + (-0.7265760135f); q = q * t + 0.7107068705f; q = q * t + (-0.142248368f); q = q * t + 0.127414796f; q = q * t;
;     const f32x2 s = (v * v) * (-0.72134752044f);
;     f32x2 e; e.x = __builtin_amdgcn_exp2f(s.x); e.y = __builtin_amdgcn_exp2f(s.y);
;     const f32x2 m = v * (q * e), r = v - m;
;     f32x2 o; o.x = v.x < 0.f ? m.x : r.x; o.y = v.y < 0.f ? m.y : r.y; return o;
; }
;     __device__ __forceinline__ void operator()(f32x4 (&acc)[2][2][4][2], const Unit& u, int wr, int wc, int fr_, int fq_) const {
;     ...
;             for (int m = 0; m < 4; ++m) { const int row = u.pm * BM + blk * 64 + m * 16 + fr;
;                 const f32x4 g0 = gelu4(acc[ai][0][m][0]), g1 = gelu4(acc[ai][0][m][1]);
;                 *(u32x4*)(ACT + (size_t)row * 5632 + jcol) = pack8(g0 * acc[ai][1][m][0], g1 * acc[ai][1][m][1]); asm volatile("" ::: "memory"); __builtin_amdgcn_sched_barrier(0); }
	v_pk_mul_f32 v[72:73], v[96:97], v[72:73]
	v_pk_mul_f32 v[74:75], v[74:75], s[50:51] op_sel_hi:[1,0]
	v_pk_mul_f32 v[96:97], v[104:105], v[72:73]
	v_pk_fma_f32 v[72:73], v[104:105], v[72:73], v[104:105] neg_lo:[1,0,0] neg_hi:[1,0,0]
	v_exp_f32_e32 v74, v74
	v_cndmask_b32_e32 v72, v72, v96, vcc
	v_cmp_gt_f32_e32 vcc, 0, v105
	v_and_b32_e32 v96, 0x7fffffff, v106
	v_exp_f32_e32 v75, v75
	v_cndmask_b32_e32 v73, v73, v97, vcc
	v_and_b32_e32 v97, 0x7fffffff, v107
	v_pk_fma_f32 v[96:97], v[96:97], s[58:59], 1.0 op_sel_hi:[1,0,0]
	v_cmp_gt_f32_e32 vcc, 0, v106
	v_rcp_f32_e32 v96, v96
	v_rcp_f32_e32 v97, v97
	v_exp_f32_e32 v101, v101
	v_add_u32_e32 v112, 32, v179
	v_pk_mul_f32 v[72:73], v[72:73], v[88:89]
	v_pk_fma_f32 v[98:99], v[96:97], s[60:61], v[128:129] op_sel_hi:[1,0,0]
	s_nop 0
	v_pk_fma_f32 v[98:99], v[96:97], v[98:99], s[62:63] op_sel_hi:[1,1,0]
	s_nop 0
	v_pk_fma_f32 v[98:99], v[96:97], v[98:99], s[64:65] op_sel_hi:[1,1,0]
	s_nop 0
	v_pk_fma_f32 v[98:99], v[96:97], v[98:99], s[66:67] op_sel_hi:[1,1,0]
	s_nop 0
	v_pk_mul_f32 v[96:97], v[96:97], v[98:99]
	s_nop 0
	v_pk_mul_f32 v[74:75], v[74:75], v[96:97]
	s_nop 0
	v_pk_mul_f32 v[96:97], v[106:107], v[74:75]
	v_pk_fma_f32 v[74:75], v[106:107], v[74:75], v[106:107] neg_lo:[1,0,0] neg_hi:[1,0,0]
	s_nop 0
	v_cndmask_b32_e32 v74, v74, v96, vcc
	v_cmp_gt_f32_e32 vcc, 0, v107
	v_and_b32_e32 v96, 0x7fffffff, v108
	s_nop 0
	v_cndmask_b32_e32 v75, v75, v97, vcc
	v_and_b32_e32 v97, 0x7fffffff, v109
	v_pk_fma_f32 v[96:97], v[96:97], s[58:59], 1.0 op_sel_hi:[1,0,0]
	v_cmp_gt_f32_e32 vcc, 0, v108
	v_rcp_f32_e32 v96, v96
	v_rcp_f32_e32 v97, v97
	v_pk_mul_f32 v[74:75], v[74:75], v[90:91]
	v_pk_fma_f32 v[98:99], v[96:97], s[60:61], v[128:129] op_sel_hi:[1,0,0]
	s_nop 0
	v_pk_fma_f32 v[98:99], v[96:97], v[98:99], s[62:63] op_sel_hi:[1,1,0]
	s_nop 0
	v_pk_fma_f32 v[98:99], v[96:97], v[98:99], s[64:65] op_sel_hi:[1,1,0]
	s_nop 0
	v_pk_fma_f32 v[98:99], v[96:97], v[98:99], s[66:67] op_sel_hi:[1,1,0]
	s_nop 0
	v_pk_mul_f32 v[96:97], v[96:97], v[98:99]
	v_pk_mul_f32 v[98:99], v[110:111], v[110:111]
	v_pk_mul_f32 v[96:97], v[100:101], v[96:97]
	v_pk_mul_f32 v[98:99], v[98:99], s[50:51] op_sel_hi:[1,0]
	v_pk_mul_f32 v[100:101], v[108:109], v[96:97]
	v_pk_fma_f32 v[96:97], v[108:109], v[96:97], v[108:109] neg_lo:[1,0,0] neg_hi:[1,0,0]
	v_exp_f32_e32 v98, v98
	v_cndmask_b32_e32 v96, v96, v100, vcc
	v_cmp_gt_f32_e32 vcc, 0, v109
	v_and_b32_e32 v100, 0x7fffffff, v110
	v_exp_f32_e32 v99, v99
	v_cndmask_b32_e32 v97, v97, v101, vcc
	v_and_b32_e32 v101, 0x7fffffff, v111
	v_pk_fma_f32 v[100:101], v[100:101], s[58:59], 1.0 op_sel_hi:[1,0,0]
	v_cmp_gt_f32_e32 vcc, 0, v110
	v_rcp_f32_e32 v100, v100
	v_rcp_f32_e32 v101, v101
	s_nop 0
	v_pk_fma_f32 v[102:103], v[100:101], s[60:61], v[128:129] op_sel_hi:[1,0,0]
	s_nop 0
	v_pk_fma_f32 v[102:103], v[100:101], v[102:103], s[62:63] op_sel_hi:[1,1,0]
	s_nop 0
	v_pk_fma_f32 v[102:103], v[100:101], v[102:103], s[64:65] op_sel_hi:[1,1,0]
	s_nop 0
	v_pk_fma_f32 v[102:103], v[100:101], v[102:103], s[66:67] op_sel_hi:[1,1,0]
	s_nop 0
	v_pk_mul_f32 v[100:101], v[100:101], v[102:103]
	s_nop 0
	v_pk_mul_f32 v[98:99], v[98:99], v[100:101]
	s_nop 0
	v_pk_mul_f32 v[100:101], v[110:111], v[98:99]
	v_pk_fma_f32 v[98:99], v[110:111], v[98:99], v[110:111] neg_lo:[1,0,0] neg_hi:[1,0,0]
	s_nop 0
	v_cndmask_b32_e32 v98, v98, v100, vcc
	v_cmp_gt_f32_e32 vcc, 0, v111
	s_nop 1
	v_cndmask_b32_e32 v99, v99, v101, vcc
	v_pk_mul_f32 v[88:89], v[98:99], v[70:71]
	v_pk_mul_f32 v[70:71], v[96:97], v[68:69]
	v_cvt_pk_bf16_f32 v68, v72, v73
	v_mad_i64_i32 v[72:73], s[0:1], v112, s93, v[76:77]
	v_cvt_pk_bf16_f32 v69, v74, v75
	v_cvt_pk_bf16_f32 v70, v70, v71
	v_cvt_pk_bf16_f32 v71, v88, v89
	v_lshl_add_u64 v[72:73], v[72:73], 0, v[78:79]
	global_store_dwordx4 v[72:73], v[68:71], off
	s_nop 1
	v_and_b32_e32 v69, 0x7fffffff, v81
	v_and_b32_e32 v68, 0x7fffffff, v80
	v_pk_fma_f32 v[68:69], v[68:69], s[58:59], 1.0 op_sel_hi:[1,0,0]
	v_pk_mul_f32 v[72:73], v[80:81], v[80:81]
	v_rcp_f32_e32 v68, v68
	v_rcp_f32_e32 v69, v69
	v_pk_mul_f32 v[72:73], v[72:73], s[50:51] op_sel_hi:[1,0]
	v_cmp_gt_f32_e32 vcc, 0, v80
	v_exp_f32_e32 v72, v72
	v_pk_fma_f32 v[70:71], v[68:69], s[60:61], v[128:129] op_sel_hi:[1,0,0]
	v_exp_f32_e32 v73, v73
	v_pk_fma_f32 v[70:71], v[68:69], v[70:71], s[62:63] op_sel_hi:[1,1,0]
	v_add_u32_e32 v88, 48, v179
	v_pk_fma_f32 v[70:71], v[68:69], v[70:71], s[64:65] op_sel_hi:[1,1,0]
	s_nop 0
	v_pk_fma_f32 v[70:71], v[68:69], v[70:71], s[66:67] op_sel_hi:[1,1,0]
	s_nop 0
	v_pk_mul_f32 v[68:69], v[68:69], v[70:71]
	v_pk_mul_f32 v[70:71], v[82:83], v[82:83]
	v_pk_mul_f32 v[68:69], v[72:73], v[68:69]
	v_pk_mul_f32 v[70:71], v[70:71], s[50:51] op_sel_hi:[1,0]
	v_pk_mul_f32 v[72:73], v[80:81], v[68:69]
	v_pk_fma_f32 v[68:69], v[80:81], v[68:69], v[80:81] neg_lo:[1,0,0] neg_hi:[1,0,0]
	v_exp_f32_e32 v70, v70
	v_cndmask_b32_e32 v68, v68, v72, vcc
	v_cmp_gt_f32_e32 vcc, 0, v81
	v_and_b32_e32 v72, 0x7fffffff, v82
	v_exp_f32_e32 v71, v71
	v_cndmask_b32_e32 v69, v69, v73, vcc
	v_and_b32_e32 v73, 0x7fffffff, v83
	v_pk_fma_f32 v[72:73], v[72:73], s[58:59], 1.0 op_sel_hi:[1,0,0]
	v_cmp_gt_f32_e32 vcc, 0, v82
	v_rcp_f32_e32 v72, v72
	v_rcp_f32_e32 v73, v73
	v_pk_mul_f32 v[80:81], v[92:93], v[92:93]
	v_pk_mul_f32 v[68:69], v[68:69], v[84:85]
	v_pk_mul_f32 v[80:81], v[80:81], s[50:51] op_sel_hi:[1,0]
	v_pk_fma_f32 v[74:75], v[72:73], s[60:61], v[128:129] op_sel_hi:[1,0,0]
	v_exp_f32_e32 v80, v80
	v_pk_fma_f32 v[74:75], v[72:73], v[74:75], s[62:63] op_sel_hi:[1,1,0]
	v_exp_f32_e32 v81, v81
	v_pk_fma_f32 v[74:75], v[72:73], v[74:75], s[64:65] op_sel_hi:[1,1,0]
	s_nop 0
	v_pk_fma_f32 v[74:75], v[72:73], v[74:75], s[66:67] op_sel_hi:[1,1,0]
; #define PG8_LAS __attribute__((address_space(3)))
; __device__ __forceinline__ f32x4 gelu4(f32x4 v) { f32x2 a = gelu_pk((f32x2){v[0], v[1]}), b = gelu_pk((f32x2){v[2], v[3]}); return (f32x4){a.x, a.y, b.x, b.y}; }
;     __device__ __forceinline__ void operator()(f32x4 (&acc)[2][2][4][2], const Unit& u, int wr, int wc, int fr_, int fq_) const {
;     ...
;         for (int ai = 0; ai < 2; ++ai) {
;             const int blk = 2 * ai + wr;
;             float rsr[4];
; #pragma unroll
;             for (int m = 0; m < 4; ++m) rsr[m] = rsL[blk * 64 + m * 16 + fr];
;             const float rs14 = blk ? rsL[blk * 64 - 2] : 0.f, rs15 = blk ? rsL[blk * 64 - 1] : 0.f;
; #pragma unroll
;             for (int bj = 0; bj < 2; ++bj)
; #pragma unroll
;                 for (int n = 0; n < 2; ++n) {
;                     const int ct = bj * HALF + wc * 32 + 8 * fq + 4 * n;
;                     const int cidx = bj * 5632 + jcol + 4 * n;
;                     const f32x4 w0 = *(const f32x4*)(cw + cidx), w1 = *(const f32x4*)(cw + 11264 + cidx), w2 = *(const f32x4*)(cw + 22528 + cidx), b4 = *(const f32x4*)(cb + cidx);
;                     f32x4 pR1 = (f32x4){0.f, 0.f, 0.f, 0.f}, pR2 = pR1;
;                     if (blk) { const f32x4 h14 = *(const PG8_LAS f32x4*)(hal + ((blk - 1) * 2 + 0) * 256 + ct) * rs14, h15 = *(const PG8_LAS f32x4*)(hal + ((blk - 1) * 2 + 1) * 256 + ct) * rs15;
;                         pR1 = h15; pR2 = (fr == 0) ? h14 : h15; }
; #pragma unroll
;                     for (int m = 0; m < 4; ++m) {
;                         const f32x4 U = acc[ai][bj][m][n] * rsr[m];
;                         f32x4 R1, R2;
; #pragma unroll
;                         for (int i = 0; i < 4; ++i) { R1[i] = dpp_ror1(U[i]); R2[i] = dpp_ror2(U[i]); }
;                         const f32x4 U1 = (fr >= 1) ? R1 : pR1, U2 = (fr >= 2) ? R2 : pR2;
;                         const f32x4 C = b4 + w0 * U2 + w1 * U1 + w2 * U;
;                         acc[ai][bj][m][n] = C; pR1 = R1; pR2 = R2;
;     ...
;             for (int m = 0; m < 4; ++m) { const int row = u.pm * BM + blk * 64 + m * 16 + fr;
;                 const f32x4 g0 = gelu4(acc[ai][0][m][0]), g1 = gelu4(acc[ai][0][m][1]);
;                 *(u32x4*)(ACT + (size_t)row * 5632 + jcol) = pack8(g0 * acc[ai][1][m][0], g1 * acc[ai][1][m][1]); asm volatile("" ::: "memory"); __builtin_amdgcn_sched_barrier(0); }
	s_nop 0
	v_pk_mul_f32 v[72:73], v[72:73], v[74:75]
	s_nop 0
	v_pk_mul_f32 v[70:71], v[70:71], v[72:73]
	s_nop 0
	v_pk_mul_f32 v[72:73], v[82:83], v[70:71]
	v_pk_fma_f32 v[70:71], v[82:83], v[70:71], v[82:83] neg_lo:[1,0,0] neg_hi:[1,0,0]
	s_nop 0
	v_cndmask_b32_e32 v70, v70, v72, vcc
	v_cmp_gt_f32_e32 vcc, 0, v83
	v_and_b32_e32 v72, 0x7fffffff, v92
	s_nop 0
	v_cndmask_b32_e32 v71, v71, v73, vcc
	v_and_b32_e32 v73, 0x7fffffff, v93
	v_pk_fma_f32 v[72:73], v[72:73], s[58:59], 1.0 op_sel_hi:[1,0,0]
	v_cmp_gt_f32_e32 vcc, 0, v92
	v_rcp_f32_e32 v72, v72
	v_rcp_f32_e32 v73, v73
	v_pk_mul_f32 v[70:71], v[70:71], v[86:87]
	v_pk_fma_f32 v[74:75], v[72:73], s[60:61], v[128:129] op_sel_hi:[1,0,0]
	s_nop 0
	v_pk_fma_f32 v[74:75], v[72:73], v[74:75], s[62:63] op_sel_hi:[1,1,0]
	s_nop 0
	v_pk_fma_f32 v[74:75], v[72:73], v[74:75], s[64:65] op_sel_hi:[1,1,0]
	s_nop 0
	v_pk_fma_f32 v[74:75], v[72:73], v[74:75], s[66:67] op_sel_hi:[1,1,0]
	s_nop 0
	v_pk_mul_f32 v[72:73], v[72:73], v[74:75]
	v_pk_mul_f32 v[74:75], v[94:95], v[94:95]
	v_pk_mul_f32 v[72:73], v[80:81], v[72:73]
	v_pk_mul_f32 v[74:75], v[74:75], s[50:51] op_sel_hi:[1,0]
	v_pk_mul_f32 v[80:81], v[92:93], v[72:73]
	v_pk_fma_f32 v[72:73], v[92:93], v[72:73], v[92:93] neg_lo:[1,0,0] neg_hi:[1,0,0]
	v_exp_f32_e32 v74, v74
	v_cndmask_b32_e32 v72, v72, v80, vcc
	v_cmp_gt_f32_e32 vcc, 0, v93
	v_and_b32_e32 v80, 0x7fffffff, v94
	v_exp_f32_e32 v75, v75
	v_cndmask_b32_e32 v73, v73, v81, vcc
	v_and_b32_e32 v81, 0x7fffffff, v95
	v_pk_fma_f32 v[80:81], v[80:81], s[58:59], 1.0 op_sel_hi:[1,0,0]
	v_cmp_gt_f32_e32 vcc, 0, v94
	v_rcp_f32_e32 v80, v80
	v_rcp_f32_e32 v81, v81
	s_nop 0
	v_pk_fma_f32 v[82:83], v[80:81], s[60:61], v[128:129] op_sel_hi:[1,0,0]
	s_nop 0
	v_pk_fma_f32 v[82:83], v[80:81], v[82:83], s[62:63] op_sel_hi:[1,1,0]
	s_nop 0
	v_pk_fma_f32 v[82:83], v[80:81], v[82:83], s[64:65] op_sel_hi:[1,1,0]
	s_nop 0
	v_pk_fma_f32 v[82:83], v[80:81], v[82:83], s[66:67] op_sel_hi:[1,1,0]
	s_nop 0
	v_pk_mul_f32 v[80:81], v[80:81], v[82:83]
	s_nop 0
	v_pk_mul_f32 v[74:75], v[74:75], v[80:81]
	s_nop 0
	v_pk_mul_f32 v[80:81], v[94:95], v[74:75]
	v_pk_fma_f32 v[74:75], v[94:95], v[74:75], v[94:95] neg_lo:[1,0,0] neg_hi:[1,0,0]
	s_nop 0
	v_cndmask_b32_e32 v74, v74, v80, vcc
	v_cmp_gt_f32_e32 vcc, 0, v95
	s_nop 1
	v_cndmask_b32_e32 v75, v75, v81, vcc
	v_pk_mul_f32 v[74:75], v[74:75], v[66:67]
	v_pk_mul_f32 v[66:67], v[72:73], v[64:65]
	v_cvt_pk_bf16_f32 v64, v68, v69
	v_mad_i64_i32 v[68:69], s[0:1], v88, s93, v[76:77]
	v_cvt_pk_bf16_f32 v65, v70, v71
	v_cvt_pk_bf16_f32 v66, v66, v67
	v_cvt_pk_bf16_f32 v67, v74, v75
	v_lshl_add_u64 v[68:69], v[68:69], 0, v[78:79]
	global_store_dwordx4 v[68:69], v[64:67], off
	global_load_dwordx4 v[80:83], v[166:167], off
	global_load_dwordx4 v[84:87], v[164:165], off
	global_load_dwordx4 v[88:91], v[168:169], off
	global_load_dwordx4 v[92:95], v[170:171], off
	v_mov_b32_e32 v65, s96
	v_add_u32_e32 v71, s97, v154
	ds_read_b64 v[66:67], v65
	ds_read_b128 v[96:99], v71
	v_add_u32_e32 v64, s89, v225
	v_add_u32_e32 v73, s14, v154
	ds_read_b128 v[100:103], v73
	ds_read2_b32 v[68:69], v64 offset1:16
	ds_read2_b32 v[64:65], v64 offset0:32 offset1:48
	s_waitcnt lgkmcnt(3)
	v_pk_mul_f32 v[74:75], v[66:67], v[98:99] op_sel_hi:[0,1]
	v_pk_mul_f32 v[96:97], v[66:67], v[96:97] op_sel_hi:[0,1]
	s_waitcnt lgkmcnt(2)
	v_pk_mul_f32 v[98:99], v[66:67], v[102:103] op_sel:[1,0]
	v_pk_mul_f32 v[100:101], v[66:67], v[100:101] op_sel:[1,0]
	v_cndmask_b32_e64 v70, v99, v75, s[10:11]
	v_cndmask_b32_e64 v72, v98, v74, s[10:11]
	v_cndmask_b32_e64 v102, v101, v97, s[10:11]
	v_cndmask_b32_e64 v103, v100, v96, s[10:11]
	s_waitcnt lgkmcnt(1)
	v_pk_mul_f32 v[62:63], v[62:63], v[68:69] op_sel_hi:[1,0]
	v_pk_mul_f32 v[60:61], v[60:61], v[68:69] op_sel_hi:[1,0]
	s_nop 0
	s_nop 1
	v_mov_b32_dpp v104, v60 row_ror:1 row_mask:0xf bank_mask:0xf
	v_mov_b32_dpp v105, v60 row_ror:2 row_mask:0xf bank_mask:0xf
	v_mov_b32_dpp v106, v61 row_ror:1 row_mask:0xf bank_mask:0xf
	v_mov_b32_dpp v107, v61 row_ror:2 row_mask:0xf bank_mask:0xf
	v_mov_b32_dpp v108, v62 row_ror:1 row_mask:0xf bank_mask:0xf
	v_mov_b32_dpp v109, v62 row_ror:2 row_mask:0xf bank_mask:0xf
	v_mov_b32_dpp v110, v63 row_ror:1 row_mask:0xf bank_mask:0xf
	v_mov_b32_dpp v111, v63 row_ror:2 row_mask:0xf bank_mask:0xf
	s_nop 0
	v_cndmask_b32_e64 v96, v100, v104, s[6:7]
	v_cndmask_b32_e64 v74, v98, v108, s[6:7]
	v_cndmask_b32_e64 v75, v99, v110, s[6:7]
	v_cndmask_b32_e64 v97, v101, v106, s[6:7]
	v_cndmask_b32_e64 v98, v72, v109, s[8:9]
	v_cndmask_b32_e64 v99, v70, v111, s[8:9]
	v_cndmask_b32_e64 v100, v103, v105, s[8:9]
	v_cndmask_b32_e64 v101, v102, v107, s[8:9]
	s_waitcnt vmcnt(2)
	v_pk_fma_f32 v[98:99], v[86:87], v[98:99], v[82:83]
	v_pk_fma_f32 v[100:101], v[84:85], v[100:101], v[80:81]
	s_waitcnt vmcnt(1)
	v_pk_fma_f32 v[74:75], v[90:91], v[74:75], v[98:99]
	v_pk_fma_f32 v[96:97], v[88:89], v[96:97], v[100:101]
	s_waitcnt vmcnt(0)
	v_pk_fma_f32 v[62:63], v[62:63], v[94:95], v[74:75]
	v_pk_fma_f32 v[60:61], v[60:61], v[92:93], v[96:97]
	s_nop 0
	v_mov_b32_e32 v70, v69
	v_pk_mul_f32 v[58:59], v[58:59], v[70:71] op_sel_hi:[1,0]
	v_pk_mul_f32 v[56:57], v[56:57], v[70:71] op_sel_hi:[1,0]
	s_nop 0
	s_nop 1
	v_mov_b32_dpp v69, v56 row_ror:1 row_mask:0xf bank_mask:0xf
	v_mov_b32_dpp v72, v56 row_ror:2 row_mask:0xf bank_mask:0xf
	v_mov_b32_dpp v102, v57 row_ror:1 row_mask:0xf bank_mask:0xf
	v_mov_b32_dpp v103, v57 row_ror:2 row_mask:0xf bank_mask:0xf
	v_mov_b32_dpp v112, v58 row_ror:1 row_mask:0xf bank_mask:0xf
	v_mov_b32_dpp v113, v58 row_ror:2 row_mask:0xf bank_mask:0xf
	v_mov_b32_dpp v114, v59 row_ror:1 row_mask:0xf bank_mask:0xf
	v_mov_b32_dpp v115, v59 row_ror:2 row_mask:0xf bank_mask:0xf
	s_nop 0
	v_cndmask_b32_e64 v100, v105, v72, s[8:9]
	v_cndmask_b32_e64 v98, v109, v113, s[8:9]
	v_cndmask_b32_e64 v99, v111, v115, s[8:9]
	v_cndmask_b32_e64 v101, v107, v103, s[8:9]
	v_cndmask_b32_e64 v74, v108, v112, s[6:7]
	v_cndmask_b32_e64 v75, v110, v114, s[6:7]
	v_cndmask_b32_e64 v96, v104, v69, s[6:7]
	v_cndmask_b32_e64 v97, v106, v102, s[6:7]
	v_pk_fma_f32 v[98:99], v[86:87], v[98:99], v[82:83]
	v_pk_fma_f32 v[100:101], v[84:85], v[100:101], v[80:81]
	v_pk_fma_f32 v[74:75], v[90:91], v[74:75], v[98:99]
	v_pk_fma_f32 v[96:97], v[88:89], v[96:97], v[100:101]
	v_pk_fma_f32 v[58:59], v[58:59], v[94:95], v[74:75]
	v_pk_fma_f32 v[56:57], v[56:57], v[92:93], v[96:97]
	s_nop 0
	s_waitcnt lgkmcnt(0)
; #define PG8_LAS __attribute__((address_space(3)))
; __device__ __forceinline__ float dpp_ror1(float x) { float r; asm volatile("s_nop 1\n\tv_mov_b32_dpp %0, %1 row_ror:1 row_mask:0xf bank_mask:0xf" : "=&v"(r) : "v"(x)); return r; }
; __device__ __forceinline__ float dpp_ror2(float x) { float r; asm volatile("s_nop 1\n\tv_mov_b32_dpp %0, %1 row_ror:2 row_mask:0xf bank_mask:0xf" : "=&v"(r) : "v"(x)); return r; }
;     __device__ __forceinline__ void operator()(f32x4 (&acc)[2][2][4][2], const Unit& u, int wr, int wc, int fr_, int fq_) const {
;     ...
;                 for (int n = 0; n < 2; ++n) {
;                     const int ct = bj * HALF + wc * 32 + 8 * fq + 4 * n;
;                     const int cidx = bj * 5632 + jcol + 4 * n;
;                     const f32x4 w0 = *(const f32x4*)(cw + cidx), w1 = *(const f32x4*)(cw + 11264 + cidx), w2 = *(const f32x4*)(cw + 22528 + cidx), b4 = *(const f32x4*)(cb + cidx);
;                     f32x4 pR1 = (f32x4){0.f, 0.f, 0.f, 0.f}, pR2 = pR1;
;                     if (blk) { const f32x4 h14 = *(const PG8_LAS f32x4*)(hal + ((blk - 1) * 2 + 0) * 256 + ct) * rs14, h15 = *(const PG8_LAS f32x4*)(hal + ((blk - 1) * 2 + 1) * 256 + ct) * rs15;
;                         pR1 = h15; pR2 = (fr == 0) ? h14 : h15; }
; #pragma unroll
;                     for (int m = 0; m < 4; ++m) {
;                         const f32x4 U = acc[ai][bj][m][n] * rsr[m];
;                         f32x4 R1, R2;
; #pragma unroll
;                         for (int i = 0; i < 4; ++i) { R1[i] = dpp_ror1(U[i]); R2[i] = dpp_ror2(U[i]); }
;                         const f32x4 U1 = (fr >= 1) ? R1 : pR1, U2 = (fr >= 2) ? R2 : pR2;
;                         const f32x4 C = b4 + w0 * U2 + w1 * U1 + w2 * U;
;                         acc[ai][bj][m][n] = C; pR1 = R1; pR2 = R2;
	v_pk_mul_f32 v[54:55], v[54:55], v[64:65] op_sel_hi:[1,0]
	v_pk_mul_f32 v[52:53], v[52:53], v[64:65] op_sel_hi:[1,0]
	s_nop 0
	s_nop 1
	v_mov_b32_dpp v104, v52 row_ror:1 row_mask:0xf bank_mask:0xf
	v_mov_b32_dpp v105, v52 row_ror:2 row_mask:0xf bank_mask:0xf
	v_mov_b32_dpp v106, v53 row_ror:1 row_mask:0xf bank_mask:0xf
	v_mov_b32_dpp v107, v53 row_ror:2 row_mask:0xf bank_mask:0xf
	v_mov_b32_dpp v108, v54 row_ror:1 row_mask:0xf bank_mask:0xf
	v_mov_b32_dpp v109, v54 row_ror:2 row_mask:0xf bank_mask:0xf
	v_mov_b32_dpp v110, v55 row_ror:1 row_mask:0xf bank_mask:0xf
	v_mov_b32_dpp v111, v55 row_ror:2 row_mask:0xf bank_mask:0xf
	s_nop 0
	v_cndmask_b32_e64 v100, v72, v105, s[8:9]
	v_cndmask_b32_e64 v98, v113, v109, s[8:9]
	v_cndmask_b32_e64 v99, v115, v111, s[8:9]
	v_cndmask_b32_e64 v101, v103, v107, s[8:9]
	v_cndmask_b32_e64 v74, v112, v108, s[6:7]
	v_cndmask_b32_e64 v75, v114, v110, s[6:7]
	v_cndmask_b32_e64 v96, v69, v104, s[6:7]
	v_cndmask_b32_e64 v97, v102, v106, s[6:7]
	v_pk_fma_f32 v[98:99], v[86:87], v[98:99], v[82:83]
	v_pk_fma_f32 v[100:101], v[84:85], v[100:101], v[80:81]
	v_pk_fma_f32 v[74:75], v[90:91], v[74:75], v[98:99]
	v_pk_fma_f32 v[96:97], v[88:89], v[96:97], v[100:101]
	v_pk_fma_f32 v[54:55], v[54:55], v[94:95], v[74:75]
	v_pk_fma_f32 v[52:53], v[52:53], v[92:93], v[96:97]
	s_nop 0
	v_mov_b32_e32 v72, v65
	v_pk_mul_f32 v[50:51], v[50:51], v[72:73] op_sel_hi:[1,0]
	v_pk_mul_f32 v[48:49], v[48:49], v[72:73] op_sel_hi:[1,0]
	s_nop 0
	s_nop 1
	v_mov_b32_dpp v65, v48 row_ror:1 row_mask:0xf bank_mask:0xf
	v_mov_b32_dpp v69, v48 row_ror:2 row_mask:0xf bank_mask:0xf
	v_mov_b32_dpp v97, v49 row_ror:1 row_mask:0xf bank_mask:0xf
	v_mov_b32_dpp v101, v49 row_ror:2 row_mask:0xf bank_mask:0xf
	v_mov_b32_dpp v74, v50 row_ror:1 row_mask:0xf bank_mask:0xf
	v_mov_b32_dpp v98, v50 row_ror:2 row_mask:0xf bank_mask:0xf
	v_mov_b32_dpp v75, v51 row_ror:1 row_mask:0xf bank_mask:0xf
	v_mov_b32_dpp v99, v51 row_ror:2 row_mask:0xf bank_mask:0xf
	s_nop 0
	v_cndmask_b32_e64 v100, v105, v69, s[8:9]
	v_cndmask_b32_e64 v98, v109, v98, s[8:9]
	v_cndmask_b32_e64 v99, v111, v99, s[8:9]
	v_cndmask_b32_e64 v101, v107, v101, s[8:9]
	v_cndmask_b32_e64 v74, v108, v74, s[6:7]
	v_cndmask_b32_e64 v75, v110, v75, s[6:7]
	v_cndmask_b32_e64 v96, v104, v65, s[6:7]
	v_cndmask_b32_e64 v97, v106, v97, s[6:7]
	v_pk_fma_f32 v[82:83], v[86:87], v[98:99], v[82:83]
	v_pk_fma_f32 v[80:81], v[84:85], v[100:101], v[80:81]
	v_pk_fma_f32 v[74:75], v[90:91], v[74:75], v[82:83]
	v_pk_fma_f32 v[80:81], v[88:89], v[96:97], v[80:81]
	v_pk_fma_f32 v[50:51], v[50:51], v[94:95], v[74:75]
	v_pk_fma_f32 v[48:49], v[48:49], v[92:93], v[80:81]
	s_nop 0
	global_load_dwordx4 v[80:83], v[164:165], off offset:16
	global_load_dwordx4 v[84:87], v[166:167], off offset:16
	global_load_dwordx4 v[88:91], v[172:173], off
	global_load_dwordx4 v[92:95], v[174:175], off
	v_pk_mul_f32 v[74:75], v[46:47], v[68:69] op_sel_hi:[1,0]
	v_pk_mul_f32 v[100:101], v[44:45], v[68:69] op_sel_hi:[1,0]
	ds_read_b128 v[44:47], v71 offset:16
	ds_read_b128 v[96:99], v73 offset:16
	s_nop 1
	v_mov_b32_dpp v65, v100 row_ror:1 row_mask:0xf bank_mask:0xf
	v_mov_b32_dpp v69, v100 row_ror:2 row_mask:0xf bank_mask:0xf
	v_mov_b32_dpp v102, v101 row_ror:1 row_mask:0xf bank_mask:0xf
	s_waitcnt lgkmcnt(1)
	v_pk_mul_f32 v[46:47], v[66:67], v[46:47] op_sel_hi:[0,1]
	v_pk_mul_f32 v[44:45], v[66:67], v[44:45] op_sel_hi:[0,1]
	s_waitcnt lgkmcnt(0)
	v_pk_mul_f32 v[98:99], v[66:67], v[98:99] op_sel:[1,0]
	v_pk_mul_f32 v[96:97], v[66:67], v[96:97] op_sel:[1,0]
	v_cndmask_b32_e64 v108, v99, v47, s[10:11]
	v_cndmask_b32_e64 v109, v98, v46, s[10:11]
	v_cndmask_b32_e64 v110, v96, v44, s[10:11]
	v_cndmask_b32_e64 v111, v97, v45, s[10:11]
	s_nop 1
	v_mov_b32_dpp v103, v101 row_ror:2 row_mask:0xf bank_mask:0xf
	v_mov_b32_dpp v104, v74 row_ror:1 row_mask:0xf bank_mask:0xf
	v_mov_b32_dpp v105, v74 row_ror:2 row_mask:0xf bank_mask:0xf
	v_mov_b32_dpp v106, v75 row_ror:1 row_mask:0xf bank_mask:0xf
	v_mov_b32_dpp v107, v75 row_ror:2 row_mask:0xf bank_mask:0xf
	v_cndmask_b32_e64 v47, v97, v102, s[6:7]
	v_cndmask_b32_e64 v44, v98, v104, s[6:7]
	v_cndmask_b32_e64 v45, v99, v106, s[6:7]
	v_cndmask_b32_e64 v46, v96, v65, s[6:7]
	v_cndmask_b32_e64 v96, v109, v105, s[8:9]
	v_cndmask_b32_e64 v97, v108, v107, s[8:9]
	v_cndmask_b32_e64 v99, v111, v103, s[8:9]
	v_cndmask_b32_e64 v98, v110, v69, s[8:9]
	s_waitcnt vmcnt(2)
	v_pk_fma_f32 v[96:97], v[82:83], v[96:97], v[86:87]
	v_pk_fma_f32 v[98:99], v[80:81], v[98:99], v[84:85]
	s_waitcnt vmcnt(1)
	v_pk_fma_f32 v[44:45], v[90:91], v[44:45], v[96:97]
	v_pk_fma_f32 v[96:97], v[88:89], v[46:47], v[98:99]
	s_waitcnt vmcnt(0)
; #define PG8_LAS __attribute__((address_space(3)))
; __device__ __forceinline__ float dpp_ror1(float x) { float r; asm volatile("s_nop 1\n\tv_mov_b32_dpp %0, %1 row_ror:1 row_mask:0xf bank_mask:0xf" : "=&v"(r) : "v"(x)); return r; }
; __device__ __forceinline__ float dpp_ror2(float x) { float r; asm volatile("s_nop 1\n\tv_mov_b32_dpp %0, %1 row_ror:2 row_mask:0xf bank_mask:0xf" : "=&v"(r) : "v"(x)); return r; }
;     __device__ __forceinline__ void operator()(f32x4 (&acc)[2][2][4][2], const Unit& u, int wr, int wc, int fr_, int fq_) const {
;     ...
;                 for (int n = 0; n < 2; ++n) {
;                     const int ct = bj * HALF + wc * 32 + 8 * fq + 4 * n;
;                     const int cidx = bj * 5632 + jcol + 4 * n;
;                     const f32x4 w0 = *(const f32x4*)(cw + cidx), w1 = *(const f32x4*)(cw + 11264 + cidx), w2 = *(const f32x4*)(cw + 22528 + cidx), b4 = *(const f32x4*)(cb + cidx);
;                     f32x4 pR1 = (f32x4){0.f, 0.f, 0.f, 0.f}, pR2 = pR1;
;                     if (blk) { const f32x4 h14 = *(const PG8_LAS f32x4*)(hal + ((blk - 1) * 2 + 0) * 256 + ct) * rs14, h15 = *(const PG8_LAS f32x4*)(hal + ((blk - 1) * 2 + 1) * 256 + ct) * rs15;
;                         pR1 = h15; pR2 = (fr == 0) ? h14 : h15; }
; #pragma unroll
;                     for (int m = 0; m < 4; ++m) {
;                         const f32x4 U = acc[ai][bj][m][n] * rsr[m];
;                         f32x4 R1, R2;
; #pragma unroll
;                         for (int i = 0; i < 4; ++i) { R1[i] = dpp_ror1(U[i]); R2[i] = dpp_ror2(U[i]); }
;                         const f32x4 U1 = (fr >= 1) ? R1 : pR1, U2 = (fr >= 2) ? R2 : pR2;
;                         const f32x4 C = b4 + w0 * U2 + w1 * U1 + w2 * U;
;                         acc[ai][bj][m][n] = C; pR1 = R1; pR2 = R2;
	v_pk_fma_f32 v[46:47], v[74:75], v[94:95], v[44:45]
	v_pk_fma_f32 v[44:45], v[100:101], v[92:93], v[96:97]
	s_nop 0
	v_pk_mul_f32 v[42:43], v[42:43], v[70:71] op_sel_hi:[1,0]
	v_pk_mul_f32 v[40:41], v[40:41], v[70:71] op_sel_hi:[1,0]
	s_nop 0
	s_nop 1
	v_mov_b32_dpp v108, v40 row_ror:1 row_mask:0xf bank_mask:0xf
	v_mov_b32_dpp v109, v40 row_ror:2 row_mask:0xf bank_mask:0xf
	v_mov_b32_dpp v110, v41 row_ror:1 row_mask:0xf bank_mask:0xf
	v_mov_b32_dpp v111, v41 row_ror:2 row_mask:0xf bank_mask:0xf
	v_mov_b32_dpp v112, v42 row_ror:1 row_mask:0xf bank_mask:0xf
	v_mov_b32_dpp v113, v42 row_ror:2 row_mask:0xf bank_mask:0xf
	v_mov_b32_dpp v114, v43 row_ror:1 row_mask:0xf bank_mask:0xf
	v_mov_b32_dpp v115, v43 row_ror:2 row_mask:0xf bank_mask:0xf
	s_nop 0
	v_cndmask_b32_e64 v100, v69, v109, s[8:9]
	v_cndmask_b32_e64 v98, v105, v113, s[8:9]
	v_cndmask_b32_e64 v99, v107, v115, s[8:9]
	v_cndmask_b32_e64 v101, v103, v111, s[8:9]
	v_cndmask_b32_e64 v74, v104, v112, s[6:7]
	v_cndmask_b32_e64 v75, v106, v114, s[6:7]
	v_cndmask_b32_e64 v96, v65, v108, s[6:7]
	v_cndmask_b32_e64 v97, v102, v110, s[6:7]
	v_pk_fma_f32 v[98:99], v[82:83], v[98:99], v[86:87]
	v_pk_fma_f32 v[100:101], v[80:81], v[100:101], v[84:85]
	v_pk_fma_f32 v[74:75], v[90:91], v[74:75], v[98:99]
	v_pk_fma_f32 v[96:97], v[88:89], v[96:97], v[100:101]
	v_pk_fma_f32 v[42:43], v[42:43], v[94:95], v[74:75]
	v_pk_fma_f32 v[40:41], v[40:41], v[92:93], v[96:97]
	s_nop 0
	v_pk_mul_f32 v[38:39], v[38:39], v[64:65] op_sel_hi:[1,0]
	v_pk_mul_f32 v[36:37], v[36:37], v[64:65] op_sel_hi:[1,0]
	s_nop 0
	s_nop 1
	v_mov_b32_dpp v65, v36 row_ror:1 row_mask:0xf bank_mask:0xf
	v_mov_b32_dpp v69, v36 row_ror:2 row_mask:0xf bank_mask:0xf
	v_mov_b32_dpp v102, v37 row_ror:1 row_mask:0xf bank_mask:0xf
	v_mov_b32_dpp v103, v37 row_ror:2 row_mask:0xf bank_mask:0xf
	v_mov_b32_dpp v104, v38 row_ror:1 row_mask:0xf bank_mask:0xf
	v_mov_b32_dpp v105, v38 row_ror:2 row_mask:0xf bank_mask:0xf
	v_mov_b32_dpp v106, v39 row_ror:1 row_mask:0xf bank_mask:0xf
	v_mov_b32_dpp v107, v39 row_ror:2 row_mask:0xf bank_mask:0xf
	s_nop 0
	v_cndmask_b32_e64 v100, v109, v69, s[8:9]
	v_cndmask_b32_e64 v98, v113, v105, s[8:9]
	v_cndmask_b32_e64 v99, v115, v107, s[8:9]
	v_cndmask_b32_e64 v101, v111, v103, s[8:9]
	v_cndmask_b32_e64 v74, v112, v104, s[6:7]
	v_cndmask_b32_e64 v75, v114, v106, s[6:7]
	v_cndmask_b32_e64 v96, v108, v65, s[6:7]
	v_cndmask_b32_e64 v97, v110, v102, s[6:7]
	v_pk_fma_f32 v[98:99], v[82:83], v[98:99], v[86:87]
	v_pk_fma_f32 v[100:101], v[80:81], v[100:101], v[84:85]
	v_pk_fma_f32 v[74:75], v[90:91], v[74:75], v[98:99]
	v_pk_fma_f32 v[96:97], v[88:89], v[96:97], v[100:101]
	v_pk_fma_f32 v[38:39], v[38:39], v[94:95], v[74:75]
	v_pk_fma_f32 v[36:37], v[36:37], v[92:93], v[96:97]
	s_nop 0
	v_pk_mul_f32 v[34:35], v[34:35], v[72:73] op_sel_hi:[1,0]
	v_pk_mul_f32 v[32:33], v[32:33], v[72:73] op_sel_hi:[1,0]
	s_nop 0
	s_nop 1
	v_mov_b32_dpp v96, v32 row_ror:1 row_mask:0xf bank_mask:0xf
	v_mov_b32_dpp v100, v32 row_ror:2 row_mask:0xf bank_mask:0xf
	v_mov_b32_dpp v97, v33 row_ror:1 row_mask:0xf bank_mask:0xf
	v_mov_b32_dpp v101, v33 row_ror:2 row_mask:0xf bank_mask:0xf
	v_mov_b32_dpp v74, v34 row_ror:1 row_mask:0xf bank_mask:0xf
	v_mov_b32_dpp v98, v34 row_ror:2 row_mask:0xf bank_mask:0xf
	v_mov_b32_dpp v75, v35 row_ror:1 row_mask:0xf bank_mask:0xf
	v_mov_b32_dpp v99, v35 row_ror:2 row_mask:0xf bank_mask:0xf
	s_nop 0
	v_cndmask_b32_e64 v100, v69, v100, s[8:9]
	v_cndmask_b32_e64 v98, v105, v98, s[8:9]
	v_cndmask_b32_e64 v99, v107, v99, s[8:9]
	v_cndmask_b32_e64 v101, v103, v101, s[8:9]
	v_cndmask_b32_e64 v74, v104, v74, s[6:7]
	v_cndmask_b32_e64 v75, v106, v75, s[6:7]
	v_cndmask_b32_e64 v96, v65, v96, s[6:7]
	v_cndmask_b32_e64 v97, v102, v97, s[6:7]
	v_pk_fma_f32 v[82:83], v[82:83], v[98:99], v[86:87]
	v_pk_fma_f32 v[80:81], v[80:81], v[100:101], v[84:85]
	v_pk_fma_f32 v[74:75], v[90:91], v[74:75], v[82:83]
	v_pk_fma_f32 v[80:81], v[88:89], v[96:97], v[80:81]
	v_pk_fma_f32 v[34:35], v[34:35], v[94:95], v[74:75]
	v_pk_fma_f32 v[32:33], v[32:33], v[92:93], v[80:81]
	s_nop 0
	global_load_dwordx4 v[80:83], v[176:177], off
	global_load_dwordx4 v[84:87], v[138:139], off
	global_load_dwordx4 v[88:91], v[140:141], off
	global_load_dwordx4 v[92:95], v[142:143], off
	v_pk_mul_f32 v[74:75], v[30:31], v[68:69] op_sel_hi:[1,0]
	v_pk_mul_f32 v[100:101], v[28:29], v[68:69] op_sel_hi:[1,0]
	ds_read_b128 v[28:31], v71 offset:512
	ds_read_b128 v[96:99], v73 offset:512
	s_nop 1
	v_mov_b32_dpp v65, v100 row_ror:1 row_mask:0xf bank_mask:0xf
	v_mov_b32_dpp v69, v100 row_ror:2 row_mask:0xf bank_mask:0xf
	v_mov_b32_dpp v102, v101 row_ror:1 row_mask:0xf bank_mask:0xf
	s_waitcnt lgkmcnt(1)
	v_pk_mul_f32 v[30:31], v[66:67], v[30:31] op_sel_hi:[0,1]
	v_pk_mul_f32 v[28:29], v[66:67], v[28:29] op_sel_hi:[0,1]
	s_waitcnt lgkmcnt(0)
	v_pk_mul_f32 v[98:99], v[66:67], v[98:99] op_sel:[1,0]
	v_pk_mul_f32 v[96:97], v[66:67], v[96:97] op_sel:[1,0]
	v_cndmask_b32_e64 v108, v99, v31, s[10:11]
	v_cndmask_b32_e64 v109, v98, v30, s[10:11]
	v_cndmask_b32_e64 v110, v96, v28, s[10:11]
	v_cndmask_b32_e64 v111, v97, v29, s[10:11]
	s_nop 1
	v_mov_b32_dpp v103, v101 row_ror:2 row_mask:0xf bank_mask:0xf
	v_mov_b32_dpp v104, v74 row_ror:1 row_mask:0xf bank_mask:0xf
	v_mov_b32_dpp v105, v74 row_ror:2 row_mask:0xf bank_mask:0xf
	v_mov_b32_dpp v106, v75 row_ror:1 row_mask:0xf bank_mask:0xf
	v_mov_b32_dpp v107, v75 row_ror:2 row_mask:0xf bank_mask:0xf
	v_cndmask_b32_e64 v31, v97, v102, s[6:7]
	v_cndmask_b32_e64 v28, v98, v104, s[6:7]
	v_cndmask_b32_e64 v29, v99, v106, s[6:7]
	v_cndmask_b32_e64 v30, v96, v65, s[6:7]
	v_cndmask_b32_e64 v96, v109, v105, s[8:9]
	v_cndmask_b32_e64 v97, v108, v107, s[8:9]
	v_cndmask_b32_e64 v99, v111, v103, s[8:9]
	v_cndmask_b32_e64 v98, v110, v69, s[8:9]
	s_waitcnt vmcnt(2)
; #define PG8_LAS __attribute__((address_space(3)))
; __device__ __forceinline__ float dpp_ror1(float x) { float r; asm volatile("s_nop 1\n\tv_mov_b32_dpp %0, %1 row_ror:1 row_mask:0xf bank_mask:0xf" : "=&v"(r) : "v"(x)); return r; }
; __device__ __forceinline__ float dpp_ror2(float x) { float r; asm volatile("s_nop 1\n\tv_mov_b32_dpp %0, %1 row_ror:2 row_mask:0xf bank_mask:0xf" : "=&v"(r) : "v"(x)); return r; }
;     __device__ __forceinline__ void operator()(f32x4 (&acc)[2][2][4][2], const Unit& u, int wr, int wc, int fr_, int fq_) const {
;     ...
;                 for (int n = 0; n < 2; ++n) {
;                     const int ct = bj * HALF + wc * 32 + 8 * fq + 4 * n;
;                     const int cidx = bj * 5632 + jcol + 4 * n;
;                     const f32x4 w0 = *(const f32x4*)(cw + cidx), w1 = *(const f32x4*)(cw + 11264 + cidx), w2 = *(const f32x4*)(cw + 22528 + cidx), b4 = *(const f32x4*)(cb + cidx);
;                     f32x4 pR1 = (f32x4){0.f, 0.f, 0.f, 0.f}, pR2 = pR1;
;                     if (blk) { const f32x4 h14 = *(const PG8_LAS f32x4*)(hal + ((blk - 1) * 2 + 0) * 256 + ct) * rs14, h15 = *(const PG8_LAS f32x4*)(hal + ((blk - 1) * 2 + 1) * 256 + ct) * rs15;
;                         pR1 = h15; pR2 = (fr == 0) ? h14 : h15; }
; #pragma unroll
;                     for (int m = 0; m < 4; ++m) {
;                         const f32x4 U = acc[ai][bj][m][n] * rsr[m];
;                         f32x4 R1, R2;
; #pragma unroll
;                         for (int i = 0; i < 4; ++i) { R1[i] = dpp_ror1(U[i]); R2[i] = dpp_ror2(U[i]); }
;                         const f32x4 U1 = (fr >= 1) ? R1 : pR1, U2 = (fr >= 2) ? R2 : pR2;
;                         const f32x4 C = b4 + w0 * U2 + w1 * U1 + w2 * U;
;                         acc[ai][bj][m][n] = C; pR1 = R1; pR2 = R2;
	v_pk_fma_f32 v[96:97], v[86:87], v[96:97], v[82:83]
	v_pk_fma_f32 v[98:99], v[84:85], v[98:99], v[80:81]
	s_waitcnt vmcnt(1)
	v_pk_fma_f32 v[28:29], v[90:91], v[28:29], v[96:97]
	v_pk_fma_f32 v[96:97], v[88:89], v[30:31], v[98:99]
	s_waitcnt vmcnt(0)
	v_pk_fma_f32 v[30:31], v[74:75], v[94:95], v[28:29]
	v_pk_fma_f32 v[28:29], v[100:101], v[92:93], v[96:97]
	s_nop 0
	v_pk_mul_f32 v[26:27], v[26:27], v[70:71] op_sel_hi:[1,0]
	v_pk_mul_f32 v[24:25], v[24:25], v[70:71] op_sel_hi:[1,0]
	s_nop 0
	s_nop 1
	v_mov_b32_dpp v108, v24 row_ror:1 row_mask:0xf bank_mask:0xf
	v_mov_b32_dpp v109, v24 row_ror:2 row_mask:0xf bank_mask:0xf
	v_mov_b32_dpp v110, v25 row_ror:1 row_mask:0xf bank_mask:0xf
	v_mov_b32_dpp v111, v25 row_ror:2 row_mask:0xf bank_mask:0xf
	v_mov_b32_dpp v112, v26 row_ror:1 row_mask:0xf bank_mask:0xf
	v_mov_b32_dpp v113, v26 row_ror:2 row_mask:0xf bank_mask:0xf
	v_mov_b32_dpp v114, v27 row_ror:1 row_mask:0xf bank_mask:0xf
	v_mov_b32_dpp v115, v27 row_ror:2 row_mask:0xf bank_mask:0xf
	s_nop 0
	v_cndmask_b32_e64 v100, v69, v109, s[8:9]
	v_cndmask_b32_e64 v98, v105, v113, s[8:9]
	v_cndmask_b32_e64 v99, v107, v115, s[8:9]
	v_cndmask_b32_e64 v101, v103, v111, s[8:9]
	v_cndmask_b32_e64 v74, v104, v112, s[6:7]
	v_cndmask_b32_e64 v75, v106, v114, s[6:7]
	v_cndmask_b32_e64 v96, v65, v108, s[6:7]
	v_cndmask_b32_e64 v97, v102, v110, s[6:7]
	v_pk_fma_f32 v[98:99], v[86:87], v[98:99], v[82:83]
	v_pk_fma_f32 v[100:101], v[84:85], v[100:101], v[80:81]
	v_pk_fma_f32 v[74:75], v[90:91], v[74:75], v[98:99]
	v_pk_fma_f32 v[96:97], v[88:89], v[96:97], v[100:101]
	v_pk_fma_f32 v[26:27], v[26:27], v[94:95], v[74:75]
	v_pk_fma_f32 v[24:25], v[24:25], v[92:93], v[96:97]
	s_nop 0
	v_pk_mul_f32 v[22:23], v[22:23], v[64:65] op_sel_hi:[1,0]
	v_pk_mul_f32 v[20:21], v[20:21], v[64:65] op_sel_hi:[1,0]
	s_nop 0
	s_nop 1
	v_mov_b32_dpp v65, v20 row_ror:1 row_mask:0xf bank_mask:0xf
	v_mov_b32_dpp v69, v20 row_ror:2 row_mask:0xf bank_mask:0xf
	v_mov_b32_dpp v102, v21 row_ror:1 row_mask:0xf bank_mask:0xf
	v_mov_b32_dpp v103, v21 row_ror:2 row_mask:0xf bank_mask:0xf
	v_mov_b32_dpp v104, v22 row_ror:1 row_mask:0xf bank_mask:0xf
	v_mov_b32_dpp v105, v22 row_ror:2 row_mask:0xf bank_mask:0xf
	v_mov_b32_dpp v106, v23 row_ror:1 row_mask:0xf bank_mask:0xf
	v_mov_b32_dpp v107, v23 row_ror:2 row_mask:0xf bank_mask:0xf
	s_nop 0
	v_cndmask_b32_e64 v100, v109, v69, s[8:9]
	v_cndmask_b32_e64 v98, v113, v105, s[8:9]
	v_cndmask_b32_e64 v99, v115, v107, s[8:9]
	v_cndmask_b32_e64 v101, v111, v103, s[8:9]
	v_cndmask_b32_e64 v74, v112, v104, s[6:7]
	v_cndmask_b32_e64 v75, v114, v106, s[6:7]
	v_cndmask_b32_e64 v96, v108, v65, s[6:7]
	v_cndmask_b32_e64 v97, v110, v102, s[6:7]
	v_pk_fma_f32 v[98:99], v[86:87], v[98:99], v[82:83]
	v_pk_fma_f32 v[100:101], v[84:85], v[100:101], v[80:81]
	v_pk_fma_f32 v[74:75], v[90:91], v[74:75], v[98:99]
	v_pk_fma_f32 v[96:97], v[88:89], v[96:97], v[100:101]
	v_pk_fma_f32 v[22:23], v[22:23], v[94:95], v[74:75]
	v_pk_fma_f32 v[20:21], v[20:21], v[92:93], v[96:97]
	s_nop 0
	v_pk_mul_f32 v[18:19], v[18:19], v[72:73] op_sel_hi:[1,0]
	v_pk_mul_f32 v[16:17], v[16:17], v[72:73] op_sel_hi:[1,0]
	s_nop 0
	s_nop 1
	v_mov_b32_dpp v96, v16 row_ror:1 row_mask:0xf bank_mask:0xf
	v_mov_b32_dpp v100, v16 row_ror:2 row_mask:0xf bank_mask:0xf
	v_mov_b32_dpp v97, v17 row_ror:1 row_mask:0xf bank_mask:0xf
	v_mov_b32_dpp v101, v17 row_ror:2 row_mask:0xf bank_mask:0xf
	v_mov_b32_dpp v74, v18 row_ror:1 row_mask:0xf bank_mask:0xf
	v_mov_b32_dpp v98, v18 row_ror:2 row_mask:0xf bank_mask:0xf
	v_mov_b32_dpp v75, v19 row_ror:1 row_mask:0xf bank_mask:0xf
	v_mov_b32_dpp v99, v19 row_ror:2 row_mask:0xf bank_mask:0xf
	s_nop 0
	v_cndmask_b32_e64 v100, v69, v100, s[8:9]
	v_cndmask_b32_e64 v98, v105, v98, s[8:9]
	v_cndmask_b32_e64 v99, v107, v99, s[8:9]
	v_cndmask_b32_e64 v101, v103, v101, s[8:9]
	v_cndmask_b32_e64 v74, v104, v74, s[6:7]
	v_cndmask_b32_e64 v75, v106, v75, s[6:7]
	v_cndmask_b32_e64 v96, v65, v96, s[6:7]
	v_cndmask_b32_e64 v97, v102, v97, s[6:7]
	v_pk_fma_f32 v[82:83], v[86:87], v[98:99], v[82:83]
	v_pk_fma_f32 v[80:81], v[84:85], v[100:101], v[80:81]
	v_pk_fma_f32 v[74:75], v[90:91], v[74:75], v[82:83]
	v_pk_fma_f32 v[80:81], v[88:89], v[96:97], v[80:81]
	v_pk_fma_f32 v[18:19], v[18:19], v[94:95], v[74:75]
	v_pk_fma_f32 v[16:17], v[16:17], v[92:93], v[80:81]
	s_nop 0
	global_load_dwordx4 v[80:83], v[136:137], off
	global_load_dwordx4 v[84:87], v[130:131], off
	global_load_dwordx4 v[88:91], v[132:133], off
	global_load_dwordx4 v[92:95], v[134:135], off
	v_pk_mul_f32 v[74:75], v[14:15], v[68:69] op_sel_hi:[1,0]
	v_pk_mul_f32 v[68:69], v[12:13], v[68:69] op_sel_hi:[1,0]
	ds_read_b128 v[12:15], v71 offset:528
	ds_read_b128 v[96:99], v73 offset:528
	s_nop 1
	v_mov_b32_dpp v65, v68 row_ror:1 row_mask:0xf bank_mask:0xf
	v_mov_b32_dpp v73, v68 row_ror:2 row_mask:0xf bank_mask:0xf
	v_mov_b32_dpp v71, v69 row_ror:1 row_mask:0xf bank_mask:0xf
	s_waitcnt lgkmcnt(1)
	v_pk_mul_f32 v[14:15], v[66:67], v[14:15] op_sel_hi:[0,1]
	v_pk_mul_f32 v[12:13], v[66:67], v[12:13] op_sel_hi:[0,1]
	s_waitcnt lgkmcnt(0)
	v_pk_mul_f32 v[98:99], v[66:67], v[98:99] op_sel:[1,0]
	v_pk_mul_f32 v[66:67], v[66:67], v[96:97] op_sel:[1,0]
	v_cndmask_b32_e64 v96, v99, v15, s[10:11]
	v_cndmask_b32_e64 v97, v98, v14, s[10:11]
	v_cndmask_b32_e64 v105, v66, v12, s[10:11]
	v_cndmask_b32_e64 v106, v67, v13, s[10:11]
	s_nop 1
	v_mov_b32_dpp v100, v69 row_ror:2 row_mask:0xf bank_mask:0xf
	v_mov_b32_dpp v101, v74 row_ror:1 row_mask:0xf bank_mask:0xf
	v_mov_b32_dpp v102, v74 row_ror:2 row_mask:0xf bank_mask:0xf
	v_mov_b32_dpp v103, v75 row_ror:1 row_mask:0xf bank_mask:0xf
	v_mov_b32_dpp v104, v75 row_ror:2 row_mask:0xf bank_mask:0xf
	v_cndmask_b32_e64 v15, v67, v71, s[6:7]
	v_cndmask_b32_e64 v14, v66, v65, s[6:7]
	v_cndmask_b32_e64 v66, v97, v102, s[8:9]
	v_cndmask_b32_e64 v67, v96, v104, s[8:9]
	v_cndmask_b32_e64 v97, v106, v100, s[8:9]
	v_cndmask_b32_e64 v96, v105, v73, s[8:9]
	v_cndmask_b32_e64 v12, v98, v101, s[6:7]
	v_cndmask_b32_e64 v13, v99, v103, s[6:7]
	s_waitcnt vmcnt(2)
; __device__ __forceinline__ u32x4 pack8(f32x4 v0, f32x4 v1) { u32x4 w; w.x = cvt_pk_bf16(v0[0], v0[1]); w.y = cvt_pk_bf16(v0[2], v0[3]); w.z = cvt_pk_bf16(v1[0], v1[1]); w.w = cvt_pk_bf16(v1[2], v1[3]); return w; }
; __device__ __forceinline__ f32x4 gelu4(f32x4 v) { f32x2 a = gelu_pk((f32x2){v[0], v[1]}), b = gelu_pk((f32x2){v[2], v[3]}); return (f32x4){a.x, a.y, b.x, b.y}; }
; __device__ __forceinline__ float dpp_ror1(float x) { float r; asm volatile("s_nop 1\n\tv_mov_b32_dpp %0, %1 row_ror:1 row_mask:0xf bank_mask:0xf" : "=&v"(r) : "v"(x)); return r; }
; __device__ __forceinline__ float dpp_ror2(float x) { float r; asm volatile("s_nop 1\n\tv_mov_b32_dpp %0, %1 row_ror:2 row_mask:0xf bank_mask:0xf" : "=&v"(r) : "v"(x)); return r; }
;     __device__ __forceinline__ void operator()(f32x4 (&acc)[2][2][4][2], const Unit& u, int wr, int wc, int fr_, int fq_) const {
;     ...
;                     for (int m = 0; m < 4; ++m) {
;                         const f32x4 U = acc[ai][bj][m][n] * rsr[m];
;                         f32x4 R1, R2;
; #pragma unroll
;                         for (int i = 0; i < 4; ++i) { R1[i] = dpp_ror1(U[i]); R2[i] = dpp_ror2(U[i]); }
;                         const f32x4 U1 = (fr >= 1) ? R1 : pR1, U2 = (fr >= 2) ? R2 : pR2;
;                         const f32x4 C = b4 + w0 * U2 + w1 * U1 + w2 * U;
;                         acc[ai][bj][m][n] = C; pR1 = R1; pR2 = R2;
;                         asm volatile("" : "+v"(acc[ai][bj][m][n]));
;                         __builtin_amdgcn_sched_barrier(0);
;                     }
;                     asm volatile("" ::: "memory");
;                 }
;             if (ai == 0 && wr == 0 && fr < 2) {
; #pragma unroll
;                 for (int bj = 0; bj < 2; ++bj)
; #pragma unroll
;                     for (int n = 0; n < 2; ++n) *(f32x4*)(TOP + ((size_t)u.pm * 2 + fr) * 11264 + u.pn * BM + bj * HALF + wc * 32 + 8 * fq + 4 * n) = acc[0][bj][0][n]; }
; #pragma unroll
;             for (int m = 0; m < 4; ++m) { const int row = u.pm * BM + blk * 64 + m * 16 + fr;
;                 const f32x4 g0 = gelu4(acc[ai][0][m][0]), g1 = gelu4(acc[ai][0][m][1]);
;                 *(u32x4*)(ACT + (size_t)row * 5632 + jcol) = pack8(g0 * acc[ai][1][m][0], g1 * acc[ai][1][m][1]); asm volatile("" ::: "memory"); __builtin_amdgcn_sched_barrier(0); }
	v_pk_fma_f32 v[66:67], v[86:87], v[66:67], v[82:83]
	v_pk_fma_f32 v[96:97], v[84:85], v[96:97], v[80:81]
	s_waitcnt vmcnt(1)
	v_pk_fma_f32 v[12:13], v[90:91], v[12:13], v[66:67]
	v_pk_fma_f32 v[66:67], v[88:89], v[14:15], v[96:97]
	s_waitcnt vmcnt(0)
	v_pk_fma_f32 v[14:15], v[74:75], v[94:95], v[12:13]
	v_pk_fma_f32 v[12:13], v[68:69], v[92:93], v[66:67]
	s_nop 0
	v_pk_mul_f32 v[10:11], v[10:11], v[70:71] op_sel_hi:[1,0]
	v_pk_mul_f32 v[8:9], v[8:9], v[70:71] op_sel_hi:[1,0]
	s_nop 0
	s_nop 1
	v_mov_b32_dpp v96, v8 row_ror:1 row_mask:0xf bank_mask:0xf
	v_mov_b32_dpp v97, v8 row_ror:2 row_mask:0xf bank_mask:0xf
	v_mov_b32_dpp v98, v9 row_ror:1 row_mask:0xf bank_mask:0xf
	v_mov_b32_dpp v99, v9 row_ror:2 row_mask:0xf bank_mask:0xf
	v_mov_b32_dpp v105, v10 row_ror:1 row_mask:0xf bank_mask:0xf
	v_mov_b32_dpp v106, v10 row_ror:2 row_mask:0xf bank_mask:0xf
	v_mov_b32_dpp v107, v11 row_ror:1 row_mask:0xf bank_mask:0xf
	v_mov_b32_dpp v108, v11 row_ror:2 row_mask:0xf bank_mask:0xf
	s_nop 0
	v_cndmask_b32_e64 v69, v71, v98, s[6:7]
	v_cndmask_b32_e64 v70, v102, v106, s[8:9]
	v_cndmask_b32_e64 v71, v104, v108, s[8:9]
	v_cndmask_b32_e64 v74, v73, v97, s[8:9]
	v_cndmask_b32_e64 v75, v100, v99, s[8:9]
	v_cndmask_b32_e64 v66, v101, v105, s[6:7]
	v_cndmask_b32_e64 v67, v103, v107, s[6:7]
	v_cndmask_b32_e64 v68, v65, v96, s[6:7]
	v_pk_fma_f32 v[70:71], v[86:87], v[70:71], v[82:83]
	v_pk_fma_f32 v[74:75], v[84:85], v[74:75], v[80:81]
	v_pk_fma_f32 v[66:67], v[90:91], v[66:67], v[70:71]
	v_pk_fma_f32 v[68:69], v[88:89], v[68:69], v[74:75]
	v_pk_fma_f32 v[10:11], v[10:11], v[94:95], v[66:67]
	v_pk_fma_f32 v[8:9], v[8:9], v[92:93], v[68:69]
	s_nop 0
	v_pk_mul_f32 v[6:7], v[6:7], v[64:65] op_sel_hi:[1,0]
	v_pk_mul_f32 v[4:5], v[4:5], v[64:65] op_sel_hi:[1,0]
	s_nop 0
	s_nop 1
	v_mov_b32_dpp v73, v4 row_ror:1 row_mask:0xf bank_mask:0xf
	v_mov_b32_dpp v74, v4 row_ror:2 row_mask:0xf bank_mask:0xf
	v_mov_b32_dpp v75, v5 row_ror:1 row_mask:0xf bank_mask:0xf
	v_mov_b32_dpp v100, v5 row_ror:2 row_mask:0xf bank_mask:0xf
	v_mov_b32_dpp v101, v6 row_ror:1 row_mask:0xf bank_mask:0xf
	v_mov_b32_dpp v102, v6 row_ror:2 row_mask:0xf bank_mask:0xf
	v_mov_b32_dpp v103, v7 row_ror:1 row_mask:0xf bank_mask:0xf
	v_mov_b32_dpp v104, v7 row_ror:2 row_mask:0xf bank_mask:0xf
	s_nop 0
	v_cndmask_b32_e64 v70, v97, v74, s[8:9]
	v_cndmask_b32_e64 v68, v106, v102, s[8:9]
	v_cndmask_b32_e64 v69, v108, v104, s[8:9]
	v_cndmask_b32_e64 v71, v99, v100, s[8:9]
	v_cndmask_b32_e64 v64, v105, v101, s[6:7]
	v_cndmask_b32_e64 v65, v107, v103, s[6:7]
	v_cndmask_b32_e64 v66, v96, v73, s[6:7]
	v_cndmask_b32_e64 v67, v98, v75, s[6:7]
	v_pk_fma_f32 v[68:69], v[86:87], v[68:69], v[82:83]
	v_pk_fma_f32 v[70:71], v[84:85], v[70:71], v[80:81]
	v_pk_fma_f32 v[64:65], v[90:91], v[64:65], v[68:69]
	v_pk_fma_f32 v[66:67], v[88:89], v[66:67], v[70:71]
	v_pk_fma_f32 v[6:7], v[6:7], v[94:95], v[64:65]
	v_pk_fma_f32 v[4:5], v[4:5], v[92:93], v[66:67]
	s_nop 0
	v_pk_mul_f32 v[2:3], v[2:3], v[72:73] op_sel_hi:[1,0]
	v_pk_mul_f32 v[0:1], v[0:1], v[72:73] op_sel_hi:[1,0]
	s_nop 0
	s_nop 1
	v_mov_b32_dpp v66, v0 row_ror:1 row_mask:0xf bank_mask:0xf
	v_mov_b32_dpp v70, v0 row_ror:2 row_mask:0xf bank_mask:0xf
	v_mov_b32_dpp v67, v1 row_ror:1 row_mask:0xf bank_mask:0xf
	v_mov_b32_dpp v71, v1 row_ror:2 row_mask:0xf bank_mask:0xf
	v_mov_b32_dpp v64, v2 row_ror:1 row_mask:0xf bank_mask:0xf
	v_mov_b32_dpp v68, v2 row_ror:2 row_mask:0xf bank_mask:0xf
	v_mov_b32_dpp v65, v3 row_ror:1 row_mask:0xf bank_mask:0xf
	v_mov_b32_dpp v69, v3 row_ror:2 row_mask:0xf bank_mask:0xf
	s_nop 0
	v_cndmask_b32_e64 v70, v74, v70, s[8:9]
	v_cndmask_b32_e64 v68, v102, v68, s[8:9]
	v_cndmask_b32_e64 v69, v104, v69, s[8:9]
	v_cndmask_b32_e64 v71, v100, v71, s[8:9]
	v_cndmask_b32_e64 v64, v101, v64, s[6:7]
	v_cndmask_b32_e64 v65, v103, v65, s[6:7]
	v_cndmask_b32_e64 v66, v73, v66, s[6:7]
	v_cndmask_b32_e64 v67, v75, v67, s[6:7]
	v_pk_fma_f32 v[68:69], v[86:87], v[68:69], v[82:83]
	v_pk_fma_f32 v[70:71], v[84:85], v[70:71], v[80:81]
	v_pk_fma_f32 v[64:65], v[90:91], v[64:65], v[68:69]
	v_pk_fma_f32 v[66:67], v[88:89], v[66:67], v[70:71]
	v_pk_fma_f32 v[2:3], v[2:3], v[94:95], v[64:65]
	v_pk_fma_f32 v[0:1], v[0:1], v[92:93], v[66:67]
	s_nop 0
	v_and_b32_e32 v67, 0x7fffffff, v61
	v_and_b32_e32 v66, 0x7fffffff, v60
	v_pk_fma_f32 v[66:67], v[66:67], s[58:59], 1.0 op_sel_hi:[1,0,0]
	v_pk_mul_f32 v[70:71], v[60:61], v[60:61]
	v_rcp_f32_e32 v66, v66
	v_rcp_f32_e32 v67, v67
	v_pk_mul_f32 v[70:71], v[70:71], s[50:51] op_sel_hi:[1,0]
	v_cmp_gt_f32_e32 vcc, 0, v60
	v_exp_f32_e32 v70, v70
	v_pk_fma_f32 v[68:69], v[66:67], s[60:61], v[128:129] op_sel_hi:[1,0,0]
	v_exp_f32_e32 v71, v71
	v_pk_fma_f32 v[68:69], v[66:67], v[68:69], s[62:63] op_sel_hi:[1,1,0]
	v_readlane_b32 s0, v244, 59
	v_pk_fma_f32 v[68:69], v[66:67], v[68:69], s[64:65] op_sel_hi:[1,1,0]
	s_nop 0
	v_pk_fma_f32 v[68:69], v[66:67], v[68:69], s[66:67] op_sel_hi:[1,1,0]
	v_add_u32_e32 v64, s0, v178
	v_pk_mul_f32 v[66:67], v[66:67], v[68:69]
	v_pk_mul_f32 v[68:69], v[62:63], v[62:63]
	v_pk_mul_f32 v[66:67], v[70:71], v[66:67]
	v_pk_mul_f32 v[68:69], v[68:69], s[50:51] op_sel_hi:[1,0]
	v_pk_mul_f32 v[70:71], v[60:61], v[66:67]
	v_pk_fma_f32 v[66:67], v[60:61], v[66:67], v[60:61] neg_lo:[1,0,0] neg_hi:[1,0,0]
	v_exp_f32_e32 v68, v68
	v_cndmask_b32_e32 v60, v66, v70, vcc
	v_cmp_gt_f32_e32 vcc, 0, v61
	v_and_b32_e32 v66, 0x7fffffff, v62
	v_exp_f32_e32 v69, v69
	v_cndmask_b32_e32 v61, v67, v71, vcc
	v_and_b32_e32 v67, 0x7fffffff, v63
	v_pk_fma_f32 v[66:67], v[66:67], s[58:59], 1.0 op_sel_hi:[1,0,0]
	v_cmp_gt_f32_e32 vcc, 0, v62
	v_rcp_f32_e32 v66, v66
	v_rcp_f32_e32 v67, v67
	v_pk_mul_f32 v[28:29], v[60:61], v[28:29]
; __device__ __forceinline__ u32x4 pack8(f32x4 v0, f32x4 v1) { u32x4 w; w.x = cvt_pk_bf16(v0[0], v0[1]); w.y = cvt_pk_bf16(v0[2], v0[3]); w.z = cvt_pk_bf16(v1[0], v1[1]); w.w = cvt_pk_bf16(v1[2], v1[3]); return w; }
; __device__ __forceinline__ f32x4 gelu4(f32x4 v) { f32x2 a = gelu_pk((f32x2){v[0], v[1]}), b = gelu_pk((f32x2){v[2], v[3]}); return (f32x4){a.x, a.y, b.x, b.y}; }
; __device__ __forceinline__ f32x2 gelu_pk(f32x2 v) {
;     const f32x2 av = __builtin_elementwise_abs(v), d = av * 0.2316418882f + 1.0f;
;     f32x2 t; t.x = __builtin_amdgcn_rcpf(d.x); t.y = __builtin_amdgcn_rcpf(d.y);
;     f32x2 q = t * 0.5307027145f + (-0.7265760135f); q = q * t + 0.7107068705f; q = q * t + (-0.142248368f); q = q * t + 0.127414796f; q = q * t;
;     const f32x2 s = (v * v) * (-0.72134752044f);
;     f32x2 e; e.x = __builtin_amdgcn_exp2f(s.x); e.y = __builtin_amdgcn_exp2f(s.y);
;     const f32x2 m = v * (q * e), r = v - m;
;     f32x2 o; o.x = v.x < 0.f ? m.x : r.x; o.y = v.y < 0.f ? m.y : r.y; return o;
; }
;     __device__ __forceinline__ void operator()(f32x4 (&acc)[2][2][4][2], const Unit& u, int wr, int wc, int fr_, int fq_) const {
;     ...
;             for (int m = 0; m < 4; ++m) { const int row = u.pm * BM + blk * 64 + m * 16 + fr;
;                 const f32x4 g0 = gelu4(acc[ai][0][m][0]), g1 = gelu4(acc[ai][0][m][1]);
;                 *(u32x4*)(ACT + (size_t)row * 5632 + jcol) = pack8(g0 * acc[ai][1][m][0], g1 * acc[ai][1][m][1]); asm volatile("" ::: "memory"); __builtin_amdgcn_sched_barrier(0); }
	v_pk_fma_f32 v[70:71], v[66:67], s[60:61], v[128:129] op_sel_hi:[1,0,0]
	s_nop 0
	v_pk_fma_f32 v[70:71], v[66:67], v[70:71], s[62:63] op_sel_hi:[1,1,0]
	s_nop 0
	v_pk_fma_f32 v[70:71], v[66:67], v[70:71], s[64:65] op_sel_hi:[1,1,0]
	s_nop 0
	v_pk_fma_f32 v[70:71], v[66:67], v[70:71], s[66:67] op_sel_hi:[1,1,0]
	s_nop 0
	v_pk_mul_f32 v[66:67], v[66:67], v[70:71]
	v_pk_mul_f32 v[70:71], v[44:45], v[44:45]
	v_pk_mul_f32 v[66:67], v[68:69], v[66:67]
	v_pk_mul_f32 v[70:71], v[70:71], s[50:51] op_sel_hi:[1,0]
	v_pk_mul_f32 v[68:69], v[62:63], v[66:67]
	v_pk_fma_f32 v[66:67], v[62:63], v[66:67], v[62:63] neg_lo:[1,0,0] neg_hi:[1,0,0]
	v_exp_f32_e32 v70, v70
	v_cndmask_b32_e32 v62, v66, v68, vcc
	v_cmp_gt_f32_e32 vcc, 0, v63
	v_and_b32_e32 v66, 0x7fffffff, v44
	v_exp_f32_e32 v71, v71
	v_cndmask_b32_e32 v63, v67, v69, vcc
	v_and_b32_e32 v67, 0x7fffffff, v45
	v_pk_fma_f32 v[66:67], v[66:67], s[58:59], 1.0 op_sel_hi:[1,0,0]
	v_cmp_gt_f32_e32 vcc, 0, v44
	v_rcp_f32_e32 v66, v66
	v_rcp_f32_e32 v67, v67
	v_pk_mul_f32 v[30:31], v[62:63], v[30:31]
	v_pk_fma_f32 v[68:69], v[66:67], s[60:61], v[128:129] op_sel_hi:[1,0,0]
	s_nop 0
	v_pk_fma_f32 v[68:69], v[66:67], v[68:69], s[62:63] op_sel_hi:[1,1,0]
	s_nop 0
	v_pk_fma_f32 v[68:69], v[66:67], v[68:69], s[64:65] op_sel_hi:[1,1,0]
	s_nop 0
	v_pk_fma_f32 v[68:69], v[66:67], v[68:69], s[66:67] op_sel_hi:[1,1,0]
	s_nop 0
	v_pk_mul_f32 v[66:67], v[66:67], v[68:69]
	v_pk_mul_f32 v[68:69], v[46:47], v[46:47]
	v_pk_mul_f32 v[66:67], v[70:71], v[66:67]
	v_pk_mul_f32 v[68:69], v[68:69], s[50:51] op_sel_hi:[1,0]
	v_pk_mul_f32 v[70:71], v[44:45], v[66:67]
	v_pk_fma_f32 v[66:67], v[44:45], v[66:67], v[44:45] neg_lo:[1,0,0] neg_hi:[1,0,0]
	v_exp_f32_e32 v68, v68
	v_cndmask_b32_e32 v44, v66, v70, vcc
	v_cmp_gt_f32_e32 vcc, 0, v45
	v_and_b32_e32 v66, 0x7fffffff, v46
	v_exp_f32_e32 v69, v69
	v_cndmask_b32_e32 v45, v67, v71, vcc
	v_and_b32_e32 v67, 0x7fffffff, v47
	v_pk_fma_f32 v[66:67], v[66:67], s[58:59], 1.0 op_sel_hi:[1,0,0]
	v_cmp_gt_f32_e32 vcc, 0, v46
	v_rcp_f32_e32 v66, v66
	v_rcp_f32_e32 v67, v67
	s_nop 0
	v_pk_fma_f32 v[70:71], v[66:67], s[60:61], v[128:129] op_sel_hi:[1,0,0]
	s_nop 0
	v_pk_fma_f32 v[70:71], v[66:67], v[70:71], s[62:63] op_sel_hi:[1,1,0]
	s_nop 0
	v_pk_fma_f32 v[70:71], v[66:67], v[70:71], s[64:65] op_sel_hi:[1,1,0]
	s_nop 0
	v_pk_fma_f32 v[70:71], v[66:67], v[70:71], s[66:67] op_sel_hi:[1,1,0]
	s_nop 0
	v_pk_mul_f32 v[66:67], v[66:67], v[70:71]
	s_nop 0
	v_pk_mul_f32 v[66:67], v[68:69], v[66:67]
	s_nop 0
	v_pk_mul_f32 v[68:69], v[46:47], v[66:67]
	v_pk_fma_f32 v[66:67], v[46:47], v[66:67], v[46:47] neg_lo:[1,0,0] neg_hi:[1,0,0]
	s_nop 0
	v_cndmask_b32_e32 v46, v66, v68, vcc
	v_cmp_gt_f32_e32 vcc, 0, v47
	s_nop 1
	v_cndmask_b32_e32 v47, v67, v69, vcc
	v_pk_mul_f32 v[46:47], v[46:47], v[14:15]
	v_pk_mul_f32 v[14:15], v[44:45], v[12:13]
	v_cvt_pk_bf16_f32 v12, v28, v29
	v_mad_i64_i32 v[28:29], s[0:1], v64, s93, v[76:77]
	v_cvt_pk_bf16_f32 v13, v30, v31
	v_cvt_pk_bf16_f32 v14, v14, v15
	v_cvt_pk_bf16_f32 v15, v46, v47
	v_lshl_add_u64 v[28:29], v[28:29], 0, v[78:79]
	global_store_dwordx4 v[28:29], v[12:15], off
	s_nop 1
	v_and_b32_e32 v13, 0x7fffffff, v57
	v_and_b32_e32 v12, 0x7fffffff, v56
	v_pk_fma_f32 v[12:13], v[12:13], s[58:59], 1.0 op_sel_hi:[1,0,0]
	v_pk_mul_f32 v[28:29], v[56:57], v[56:57]
	v_rcp_f32_e32 v12, v12
	v_rcp_f32_e32 v13, v13
	v_pk_mul_f32 v[28:29], v[28:29], s[50:51] op_sel_hi:[1,0]
	v_cmp_gt_f32_e32 vcc, 0, v56
	v_exp_f32_e32 v28, v28
	v_pk_fma_f32 v[14:15], v[12:13], s[60:61], v[128:129] op_sel_hi:[1,0,0]
	v_exp_f32_e32 v29, v29
	v_pk_fma_f32 v[14:15], v[12:13], v[14:15], s[62:63] op_sel_hi:[1,1,0]
	v_pk_mul_f32 v[44:45], v[40:41], v[40:41]
	v_pk_fma_f32 v[14:15], v[12:13], v[14:15], s[64:65] op_sel_hi:[1,1,0]
	v_pk_mul_f32 v[44:45], v[44:45], s[50:51] op_sel_hi:[1,0]
	v_pk_fma_f32 v[14:15], v[12:13], v[14:15], s[66:67] op_sel_hi:[1,1,0]
	v_exp_f32_e32 v44, v44
	v_pk_mul_f32 v[12:13], v[12:13], v[14:15]
	v_pk_mul_f32 v[14:15], v[58:59], v[58:59]
	v_pk_mul_f32 v[12:13], v[28:29], v[12:13]
	v_pk_mul_f32 v[14:15], v[14:15], s[50:51] op_sel_hi:[1,0]
	v_pk_mul_f32 v[28:29], v[56:57], v[12:13]
	v_pk_fma_f32 v[12:13], v[56:57], v[12:13], v[56:57] neg_lo:[1,0,0] neg_hi:[1,0,0]
	v_exp_f32_e32 v14, v14
	v_cndmask_b32_e32 v12, v12, v28, vcc
	v_cmp_gt_f32_e32 vcc, 0, v57
	v_and_b32_e32 v28, 0x7fffffff, v58
	v_exp_f32_e32 v15, v15
	v_cndmask_b32_e32 v13, v13, v29, vcc
	v_and_b32_e32 v29, 0x7fffffff, v59
	v_pk_fma_f32 v[28:29], v[28:29], s[58:59], 1.0 op_sel_hi:[1,0,0]
	v_cmp_gt_f32_e32 vcc, 0, v58
	v_rcp_f32_e32 v28, v28
	v_rcp_f32_e32 v29, v29
	v_exp_f32_e32 v45, v45
	v_add_u32_e32 v46, 16, v64
	v_pk_mul_f32 v[12:13], v[12:13], v[24:25]
	v_pk_fma_f32 v[30:31], v[28:29], s[60:61], v[128:129] op_sel_hi:[1,0,0]
	s_nop 0
	v_pk_fma_f32 v[30:31], v[28:29], v[30:31], s[62:63] op_sel_hi:[1,1,0]
	s_nop 0
	v_pk_fma_f32 v[30:31], v[28:29], v[30:31], s[64:65] op_sel_hi:[1,1,0]
	s_nop 0
	v_pk_fma_f32 v[30:31], v[28:29], v[30:31], s[66:67] op_sel_hi:[1,1,0]
	s_nop 0
	v_pk_mul_f32 v[28:29], v[28:29], v[30:31]
	s_nop 0
	v_pk_mul_f32 v[14:15], v[14:15], v[28:29]
	s_nop 0
	v_pk_mul_f32 v[28:29], v[58:59], v[14:15]
	v_pk_fma_f32 v[14:15], v[58:59], v[14:15], v[58:59] neg_lo:[1,0,0] neg_hi:[1,0,0]
	s_nop 0
	v_cndmask_b32_e32 v14, v14, v28, vcc
	v_cmp_gt_f32_e32 vcc, 0, v59
	v_and_b32_e32 v28, 0x7fffffff, v40
	s_nop 0
	v_cndmask_b32_e32 v15, v15, v29, vcc
	v_and_b32_e32 v29, 0x7fffffff, v41
	v_pk_fma_f32 v[28:29], v[28:29], s[58:59], 1.0 op_sel_hi:[1,0,0]
	v_cmp_gt_f32_e32 vcc, 0, v40
	v_rcp_f32_e32 v28, v28
	v_rcp_f32_e32 v29, v29
	v_pk_mul_f32 v[14:15], v[14:15], v[26:27]
; __device__ __forceinline__ u32x4 pack8(f32x4 v0, f32x4 v1) { u32x4 w; w.x = cvt_pk_bf16(v0[0], v0[1]); w.y = cvt_pk_bf16(v0[2], v0[3]); w.z = cvt_pk_bf16(v1[0], v1[1]); w.w = cvt_pk_bf16(v1[2], v1[3]); return w; }
; __device__ __forceinline__ f32x4 gelu4(f32x4 v) { f32x2 a = gelu_pk((f32x2){v[0], v[1]}), b = gelu_pk((f32x2){v[2], v[3]}); return (f32x4){a.x, a.y, b.x, b.y}; }
; __device__ __forceinline__ f32x2 gelu_pk(f32x2 v) {
;     const f32x2 av = __builtin_elementwise_abs(v), d = av * 0.2316418882f + 1.0f;
;     f32x2 t; t.x = __builtin_amdgcn_rcpf(d.x); t.y = __builtin_amdgcn_rcpf(d.y);
;     f32x2 q = t * 0.5307027145f + (-0.7265760135f); q = q * t + 0.7107068705f; q = q * t + (-0.142248368f); q = q * t + 0.127414796f; q = q * t;
;     const f32x2 s = (v * v) * (-0.72134752044f);
;     f32x2 e; e.x = __builtin_amdgcn_exp2f(s.x); e.y = __builtin_amdgcn_exp2f(s.y);
;     const f32x2 m = v * (q * e), r = v - m;
;     f32x2 o; o.x = v.x < 0.f ? m.x : r.x; o.y = v.y < 0.f ? m.y : r.y; return o;
; }
;     __device__ __forceinline__ void operator()(f32x4 (&acc)[2][2][4][2], const Unit& u, int wr, int wc, int fr_, int fq_) const {
;     ...
;             for (int m = 0; m < 4; ++m) { const int row = u.pm * BM + blk * 64 + m * 16 + fr;
;                 const f32x4 g0 = gelu4(acc[ai][0][m][0]), g1 = gelu4(acc[ai][0][m][1]);
;                 *(u32x4*)(ACT + (size_t)row * 5632 + jcol) = pack8(g0 * acc[ai][1][m][0], g1 * acc[ai][1][m][1]); asm volatile("" ::: "memory"); __builtin_amdgcn_sched_barrier(0); }
	v_pk_fma_f32 v[30:31], v[28:29], s[60:61], v[128:129] op_sel_hi:[1,0,0]
	s_nop 0
	v_pk_fma_f32 v[30:31], v[28:29], v[30:31], s[62:63] op_sel_hi:[1,1,0]
	s_nop 0
	v_pk_fma_f32 v[30:31], v[28:29], v[30:31], s[64:65] op_sel_hi:[1,1,0]
	s_nop 0
	v_pk_fma_f32 v[30:31], v[28:29], v[30:31], s[66:67] op_sel_hi:[1,1,0]
	s_nop 0
	v_pk_mul_f32 v[28:29], v[28:29], v[30:31]
	v_pk_mul_f32 v[30:31], v[42:43], v[42:43]
	v_pk_mul_f32 v[28:29], v[44:45], v[28:29]
	v_pk_mul_f32 v[30:31], v[30:31], s[50:51] op_sel_hi:[1,0]
	v_pk_mul_f32 v[44:45], v[40:41], v[28:29]
	v_pk_fma_f32 v[28:29], v[40:41], v[28:29], v[40:41] neg_lo:[1,0,0] neg_hi:[1,0,0]
	v_and_b32_e32 v40, 0x7fffffff, v42
	v_cndmask_b32_e32 v28, v28, v44, vcc
	v_cmp_gt_f32_e32 vcc, 0, v41
	v_and_b32_e32 v41, 0x7fffffff, v43
	v_pk_fma_f32 v[40:41], v[40:41], s[58:59], 1.0 op_sel_hi:[1,0,0]
	v_cndmask_b32_e32 v29, v29, v45, vcc
	v_rcp_f32_e32 v40, v40
	v_rcp_f32_e32 v41, v41
	v_exp_f32_e32 v30, v30
	v_exp_f32_e32 v31, v31
	v_cmp_gt_f32_e32 vcc, 0, v42
	v_pk_fma_f32 v[44:45], v[40:41], s[60:61], v[128:129] op_sel_hi:[1,0,0]
	s_nop 0
	v_pk_fma_f32 v[44:45], v[40:41], v[44:45], s[62:63] op_sel_hi:[1,1,0]
	s_nop 0
	v_pk_fma_f32 v[44:45], v[40:41], v[44:45], s[64:65] op_sel_hi:[1,1,0]
	s_nop 0
	v_pk_fma_f32 v[44:45], v[40:41], v[44:45], s[66:67] op_sel_hi:[1,1,0]
	s_nop 0
	v_pk_mul_f32 v[40:41], v[40:41], v[44:45]
	s_nop 0
	v_pk_mul_f32 v[30:31], v[30:31], v[40:41]
	s_nop 0
	v_pk_mul_f32 v[40:41], v[42:43], v[30:31]
	v_pk_fma_f32 v[30:31], v[42:43], v[30:31], v[42:43] neg_lo:[1,0,0] neg_hi:[1,0,0]
	s_nop 0
	v_cndmask_b32_e32 v30, v30, v40, vcc
	v_cmp_gt_f32_e32 vcc, 0, v43
	s_nop 1
	v_cndmask_b32_e32 v31, v31, v41, vcc
	v_pk_mul_f32 v[24:25], v[30:31], v[10:11]
	v_pk_mul_f32 v[10:11], v[28:29], v[8:9]
	v_cvt_pk_bf16_f32 v8, v12, v13
	v_mad_i64_i32 v[12:13], s[0:1], v46, s93, v[76:77]
	v_cvt_pk_bf16_f32 v9, v14, v15
	v_cvt_pk_bf16_f32 v10, v10, v11
	v_cvt_pk_bf16_f32 v11, v24, v25
	v_lshl_add_u64 v[12:13], v[12:13], 0, v[78:79]
	global_store_dwordx4 v[12:13], v[8:11], off
	s_nop 1
	v_and_b32_e32 v9, 0x7fffffff, v53
	v_and_b32_e32 v8, 0x7fffffff, v52
	v_pk_fma_f32 v[8:9], v[8:9], s[58:59], 1.0 op_sel_hi:[1,0,0]
	v_pk_mul_f32 v[12:13], v[52:53], v[52:53]
	v_rcp_f32_e32 v8, v8
	v_rcp_f32_e32 v9, v9
	v_pk_mul_f32 v[12:13], v[12:13], s[50:51] op_sel_hi:[1,0]
	v_cmp_gt_f32_e32 vcc, 0, v52
	v_exp_f32_e32 v12, v12
	v_pk_fma_f32 v[10:11], v[8:9], s[60:61], v[128:129] op_sel_hi:[1,0,0]
	v_exp_f32_e32 v13, v13
	v_pk_fma_f32 v[10:11], v[8:9], v[10:11], s[62:63] op_sel_hi:[1,1,0]
	v_pk_mul_f32 v[24:25], v[36:37], v[36:37]
	v_pk_fma_f32 v[10:11], v[8:9], v[10:11], s[64:65] op_sel_hi:[1,1,0]
	v_pk_mul_f32 v[24:25], v[24:25], s[50:51] op_sel_hi:[1,0]
	v_pk_fma_f32 v[10:11], v[8:9], v[10:11], s[66:67] op_sel_hi:[1,1,0]
	v_exp_f32_e32 v24, v24
	v_pk_mul_f32 v[8:9], v[8:9], v[10:11]
	v_pk_mul_f32 v[10:11], v[54:55], v[54:55]
	v_pk_mul_f32 v[8:9], v[12:13], v[8:9]
	v_pk_mul_f32 v[10:11], v[10:11], s[50:51] op_sel_hi:[1,0]
	v_pk_mul_f32 v[12:13], v[52:53], v[8:9]
	v_pk_fma_f32 v[8:9], v[52:53], v[8:9], v[52:53] neg_lo:[1,0,0] neg_hi:[1,0,0]
	v_exp_f32_e32 v10, v10
	v_cndmask_b32_e32 v8, v8, v12, vcc
	v_cmp_gt_f32_e32 vcc, 0, v53
	v_and_b32_e32 v12, 0x7fffffff, v54
	v_exp_f32_e32 v11, v11
	v_cndmask_b32_e32 v9, v9, v13, vcc
	v_and_b32_e32 v13, 0x7fffffff, v55
	v_pk_fma_f32 v[12:13], v[12:13], s[58:59], 1.0 op_sel_hi:[1,0,0]
	v_cmp_gt_f32_e32 vcc, 0, v54
	v_rcp_f32_e32 v12, v12
	v_rcp_f32_e32 v13, v13
	v_exp_f32_e32 v25, v25
	v_add_u32_e32 v28, 32, v64
	v_pk_mul_f32 v[8:9], v[8:9], v[20:21]
	v_pk_fma_f32 v[14:15], v[12:13], s[60:61], v[128:129] op_sel_hi:[1,0,0]
	s_nop 0
	v_pk_fma_f32 v[14:15], v[12:13], v[14:15], s[62:63] op_sel_hi:[1,1,0]
	s_nop 0
	v_pk_fma_f32 v[14:15], v[12:13], v[14:15], s[64:65] op_sel_hi:[1,1,0]
	s_nop 0
	v_pk_fma_f32 v[14:15], v[12:13], v[14:15], s[66:67] op_sel_hi:[1,1,0]
	s_nop 0
	v_pk_mul_f32 v[12:13], v[12:13], v[14:15]
	s_nop 0
	v_pk_mul_f32 v[10:11], v[10:11], v[12:13]
	s_nop 0
	v_pk_mul_f32 v[12:13], v[54:55], v[10:11]
	v_pk_fma_f32 v[10:11], v[54:55], v[10:11], v[54:55] neg_lo:[1,0,0] neg_hi:[1,0,0]
	s_nop 0
	v_cndmask_b32_e32 v10, v10, v12, vcc
	v_cmp_gt_f32_e32 vcc, 0, v55
	v_and_b32_e32 v12, 0x7fffffff, v36
	s_nop 0
	v_cndmask_b32_e32 v11, v11, v13, vcc
	v_and_b32_e32 v13, 0x7fffffff, v37
	v_pk_fma_f32 v[12:13], v[12:13], s[58:59], 1.0 op_sel_hi:[1,0,0]
	v_cmp_gt_f32_e32 vcc, 0, v36
	v_rcp_f32_e32 v12, v12
	v_rcp_f32_e32 v13, v13
	v_pk_mul_f32 v[10:11], v[10:11], v[22:23]
	v_pk_fma_f32 v[14:15], v[12:13], s[60:61], v[128:129] op_sel_hi:[1,0,0]
	s_nop 0
	v_pk_fma_f32 v[14:15], v[12:13], v[14:15], s[62:63] op_sel_hi:[1,1,0]
	s_nop 0
	v_pk_fma_f32 v[14:15], v[12:13], v[14:15], s[64:65] op_sel_hi:[1,1,0]
	s_nop 0
	v_pk_fma_f32 v[14:15], v[12:13], v[14:15], s[66:67] op_sel_hi:[1,1,0]
	s_nop 0
	v_pk_mul_f32 v[12:13], v[12:13], v[14:15]
	v_pk_mul_f32 v[14:15], v[38:39], v[38:39]
	v_pk_mul_f32 v[12:13], v[24:25], v[12:13]
	v_pk_mul_f32 v[14:15], v[14:15], s[50:51] op_sel_hi:[1,0]
	v_pk_mul_f32 v[24:25], v[36:37], v[12:13]
	v_pk_fma_f32 v[12:13], v[36:37], v[12:13], v[36:37] neg_lo:[1,0,0] neg_hi:[1,0,0]
	v_exp_f32_e32 v14, v14
	v_cndmask_b32_e32 v12, v12, v24, vcc
	v_cmp_gt_f32_e32 vcc, 0, v37
	v_and_b32_e32 v24, 0x7fffffff, v38
	v_exp_f32_e32 v15, v15
	v_cndmask_b32_e32 v13, v13, v25, vcc
	v_and_b32_e32 v25, 0x7fffffff, v39
	v_pk_fma_f32 v[24:25], v[24:25], s[58:59], 1.0 op_sel_hi:[1,0,0]
	v_cmp_gt_f32_e32 vcc, 0, v38
	v_rcp_f32_e32 v24, v24
	v_rcp_f32_e32 v25, v25
	s_nop 0
; __device__ __forceinline__ u32x4 pack8(f32x4 v0, f32x4 v1) { u32x4 w; w.x = cvt_pk_bf16(v0[0], v0[1]); w.y = cvt_pk_bf16(v0[2], v0[3]); w.z = cvt_pk_bf16(v1[0], v1[1]); w.w = cvt_pk_bf16(v1[2], v1[3]); return w; }
; __device__ __forceinline__ f32x4 gelu4(f32x4 v) { f32x2 a = gelu_pk((f32x2){v[0], v[1]}), b = gelu_pk((f32x2){v[2], v[3]}); return (f32x4){a.x, a.y, b.x, b.y}; }
; __device__ __forceinline__ f32x2 gelu_pk(f32x2 v) {
;     const f32x2 av = __builtin_elementwise_abs(v), d = av * 0.2316418882f + 1.0f;
;     f32x2 t; t.x = __builtin_amdgcn_rcpf(d.x); t.y = __builtin_amdgcn_rcpf(d.y);
;     f32x2 q = t * 0.5307027145f + (-0.7265760135f); q = q * t + 0.7107068705f; q = q * t + (-0.142248368f); q = q * t + 0.127414796f; q = q * t;
;     const f32x2 s = (v * v) * (-0.72134752044f);
;     f32x2 e; e.x = __builtin_amdgcn_exp2f(s.x); e.y = __builtin_amdgcn_exp2f(s.y);
;     const f32x2 m = v * (q * e), r = v - m;
;     f32x2 o; o.x = v.x < 0.f ? m.x : r.x; o.y = v.y < 0.f ? m.y : r.y; return o;
; }
;     __device__ __forceinline__ void operator()(f32x4 (&acc)[2][2][4][2], const Unit& u, int wr, int wc, int fr_, int fq_) const {
;     ...
;             for (int m = 0; m < 4; ++m) { const int row = u.pm * BM + blk * 64 + m * 16 + fr;
;                 const f32x4 g0 = gelu4(acc[ai][0][m][0]), g1 = gelu4(acc[ai][0][m][1]);
;                 *(u32x4*)(ACT + (size_t)row * 5632 + jcol) = pack8(g0 * acc[ai][1][m][0], g1 * acc[ai][1][m][1]); asm volatile("" ::: "memory"); __builtin_amdgcn_sched_barrier(0); }
	v_pk_fma_f32 v[26:27], v[24:25], s[60:61], v[128:129] op_sel_hi:[1,0,0]
	s_nop 0
	v_pk_fma_f32 v[26:27], v[24:25], v[26:27], s[62:63] op_sel_hi:[1,1,0]
	s_nop 0
	v_pk_fma_f32 v[26:27], v[24:25], v[26:27], s[64:65] op_sel_hi:[1,1,0]
	s_nop 0
	v_pk_fma_f32 v[26:27], v[24:25], v[26:27], s[66:67] op_sel_hi:[1,1,0]
	s_nop 0
	v_pk_mul_f32 v[24:25], v[24:25], v[26:27]
	s_nop 0
	v_pk_mul_f32 v[14:15], v[14:15], v[24:25]
	s_nop 0
	v_pk_mul_f32 v[24:25], v[38:39], v[14:15]
	v_pk_fma_f32 v[14:15], v[38:39], v[14:15], v[38:39] neg_lo:[1,0,0] neg_hi:[1,0,0]
	s_nop 0
	v_cndmask_b32_e32 v14, v14, v24, vcc
	v_cmp_gt_f32_e32 vcc, 0, v39
	s_nop 1
	v_cndmask_b32_e32 v15, v15, v25, vcc
	v_pk_mul_f32 v[14:15], v[14:15], v[6:7]
	v_pk_mul_f32 v[6:7], v[12:13], v[4:5]
	v_cvt_pk_bf16_f32 v4, v8, v9
	v_mad_i64_i32 v[8:9], s[0:1], v28, s93, v[76:77]
	v_cvt_pk_bf16_f32 v5, v10, v11
	v_cvt_pk_bf16_f32 v6, v6, v7
	v_cvt_pk_bf16_f32 v7, v14, v15
	v_lshl_add_u64 v[8:9], v[8:9], 0, v[78:79]
	global_store_dwordx4 v[8:9], v[4:7], off
	s_nop 1
	v_and_b32_e32 v5, 0x7fffffff, v49
	v_and_b32_e32 v4, 0x7fffffff, v48
	v_pk_fma_f32 v[4:5], v[4:5], s[58:59], 1.0 op_sel_hi:[1,0,0]
	v_pk_mul_f32 v[8:9], v[48:49], v[48:49]
	v_rcp_f32_e32 v4, v4
	v_rcp_f32_e32 v5, v5
	v_pk_mul_f32 v[8:9], v[8:9], s[50:51] op_sel_hi:[1,0]
	v_cmp_gt_f32_e32 vcc, 0, v48
	v_exp_f32_e32 v8, v8
	v_pk_fma_f32 v[6:7], v[4:5], s[60:61], v[128:129] op_sel_hi:[1,0,0]
	v_exp_f32_e32 v9, v9
	v_pk_fma_f32 v[6:7], v[4:5], v[6:7], s[62:63] op_sel_hi:[1,1,0]
	v_pk_mul_f32 v[12:13], v[32:33], v[32:33]
	v_pk_fma_f32 v[6:7], v[4:5], v[6:7], s[64:65] op_sel_hi:[1,1,0]
	v_pk_mul_f32 v[12:13], v[12:13], s[50:51] op_sel_hi:[1,0]
	v_pk_fma_f32 v[6:7], v[4:5], v[6:7], s[66:67] op_sel_hi:[1,1,0]
	v_exp_f32_e32 v12, v12
	v_pk_mul_f32 v[4:5], v[4:5], v[6:7]
	v_pk_mul_f32 v[6:7], v[50:51], v[50:51]
	v_pk_mul_f32 v[4:5], v[8:9], v[4:5]
	v_pk_mul_f32 v[6:7], v[6:7], s[50:51] op_sel_hi:[1,0]
	v_pk_mul_f32 v[8:9], v[48:49], v[4:5]
	v_pk_fma_f32 v[4:5], v[48:49], v[4:5], v[48:49] neg_lo:[1,0,0] neg_hi:[1,0,0]
	v_exp_f32_e32 v6, v6
	v_cndmask_b32_e32 v4, v4, v8, vcc
	v_cmp_gt_f32_e32 vcc, 0, v49
	v_and_b32_e32 v8, 0x7fffffff, v50
	v_exp_f32_e32 v7, v7
	v_cndmask_b32_e32 v5, v5, v9, vcc
	v_and_b32_e32 v9, 0x7fffffff, v51
	v_pk_fma_f32 v[8:9], v[8:9], s[58:59], 1.0 op_sel_hi:[1,0,0]
	v_cmp_gt_f32_e32 vcc, 0, v50
	v_rcp_f32_e32 v8, v8
	v_rcp_f32_e32 v9, v9
	v_exp_f32_e32 v13, v13
	v_add_u32_e32 v20, 48, v64
	v_pk_mul_f32 v[4:5], v[4:5], v[16:17]
	v_pk_fma_f32 v[10:11], v[8:9], s[60:61], v[128:129] op_sel_hi:[1,0,0]
	s_nop 0
	v_pk_fma_f32 v[10:11], v[8:9], v[10:11], s[62:63] op_sel_hi:[1,1,0]
	s_nop 0
	v_pk_fma_f32 v[10:11], v[8:9], v[10:11], s[64:65] op_sel_hi:[1,1,0]
	s_nop 0
	v_pk_fma_f32 v[10:11], v[8:9], v[10:11], s[66:67] op_sel_hi:[1,1,0]
	s_nop 0
	v_pk_mul_f32 v[8:9], v[8:9], v[10:11]
	s_nop 0
	v_pk_mul_f32 v[6:7], v[6:7], v[8:9]
	s_nop 0
	v_pk_mul_f32 v[8:9], v[50:51], v[6:7]
	v_pk_fma_f32 v[6:7], v[50:51], v[6:7], v[50:51] neg_lo:[1,0,0] neg_hi:[1,0,0]
	s_nop 0
	v_cndmask_b32_e32 v6, v6, v8, vcc
	v_cmp_gt_f32_e32 vcc, 0, v51
	v_and_b32_e32 v8, 0x7fffffff, v32
	s_nop 0
	v_cndmask_b32_e32 v7, v7, v9, vcc
	v_and_b32_e32 v9, 0x7fffffff, v33
	v_pk_fma_f32 v[8:9], v[8:9], s[58:59], 1.0 op_sel_hi:[1,0,0]
	v_cmp_gt_f32_e32 vcc, 0, v32
	v_rcp_f32_e32 v8, v8
	v_rcp_f32_e32 v9, v9
	v_pk_mul_f32 v[6:7], v[6:7], v[18:19]
	v_pk_fma_f32 v[10:11], v[8:9], s[60:61], v[128:129] op_sel_hi:[1,0,0]
	s_nop 0
	v_pk_fma_f32 v[10:11], v[8:9], v[10:11], s[62:63] op_sel_hi:[1,1,0]
	s_nop 0
	v_pk_fma_f32 v[10:11], v[8:9], v[10:11], s[64:65] op_sel_hi:[1,1,0]
	s_nop 0
	v_pk_fma_f32 v[10:11], v[8:9], v[10:11], s[66:67] op_sel_hi:[1,1,0]
	s_nop 0
	v_pk_mul_f32 v[8:9], v[8:9], v[10:11]
	v_pk_mul_f32 v[10:11], v[34:35], v[34:35]
	v_pk_mul_f32 v[8:9], v[12:13], v[8:9]
	v_pk_mul_f32 v[10:11], v[10:11], s[50:51] op_sel_hi:[1,0]
	v_pk_mul_f32 v[12:13], v[32:33], v[8:9]
	v_pk_fma_f32 v[8:9], v[32:33], v[8:9], v[32:33] neg_lo:[1,0,0] neg_hi:[1,0,0]
	v_exp_f32_e32 v10, v10
	v_cndmask_b32_e32 v8, v8, v12, vcc
	v_cmp_gt_f32_e32 vcc, 0, v33
	v_and_b32_e32 v12, 0x7fffffff, v34
	v_exp_f32_e32 v11, v11
	v_cndmask_b32_e32 v9, v9, v13, vcc
	v_and_b32_e32 v13, 0x7fffffff, v35
	v_pk_fma_f32 v[12:13], v[12:13], s[58:59], 1.0 op_sel_hi:[1,0,0]
	v_cmp_gt_f32_e32 vcc, 0, v34
	v_rcp_f32_e32 v12, v12
	v_rcp_f32_e32 v13, v13
	s_nop 0
	v_pk_fma_f32 v[14:15], v[12:13], s[60:61], v[128:129] op_sel_hi:[1,0,0]
	s_nop 0
	v_pk_fma_f32 v[14:15], v[12:13], v[14:15], s[62:63] op_sel_hi:[1,1,0]
	s_nop 0
	v_pk_fma_f32 v[14:15], v[12:13], v[14:15], s[64:65] op_sel_hi:[1,1,0]
	s_nop 0
	v_pk_fma_f32 v[14:15], v[12:13], v[14:15], s[66:67] op_sel_hi:[1,1,0]
	s_nop 0
	v_pk_mul_f32 v[12:13], v[12:13], v[14:15]
	s_nop 0
	v_pk_mul_f32 v[10:11], v[10:11], v[12:13]
	s_nop 0
	v_pk_mul_f32 v[12:13], v[34:35], v[10:11]
	v_pk_fma_f32 v[10:11], v[34:35], v[10:11], v[34:35] neg_lo:[1,0,0] neg_hi:[1,0,0]
	s_nop 0
	v_cndmask_b32_e32 v10, v10, v12, vcc
	v_cmp_gt_f32_e32 vcc, 0, v35
	s_nop 1
	v_cndmask_b32_e32 v11, v11, v13, vcc
	v_pk_mul_f32 v[10:11], v[10:11], v[2:3]
	v_pk_mul_f32 v[2:3], v[8:9], v[0:1]
	v_cvt_pk_bf16_f32 v0, v4, v5
	v_mad_i64_i32 v[4:5], s[0:1], v20, s93, v[76:77]
	v_cvt_pk_bf16_f32 v1, v6, v7
	v_cvt_pk_bf16_f32 v2, v2, v3
	v_cvt_pk_bf16_f32 v3, v10, v11
	v_lshl_add_u64 v[4:5], v[4:5], 0, v[78:79]
	global_store_dwordx4 v[4:5], v[0:3], off
	s_andn2_b64 vcc, exec, s[4:5]
	s_mov_b64 s[0:1], -1
	s_cbranch_vccnz .LBB0_1697
	s_andn2_b64 vcc, exec, s[18:19]
	s_cbranch_vccnz .LBB0_1696
	s_barrier
	s_branch .LBB0_1696
